# attention: output partials reduce-scattered across lane groups (even groups keep elements 0..7, odd 8..15) before the two cross-row exchanges, unmasked index prefetch when all 256 keys exist
# speedup vs baseline: 1.0108x; 1.0108x over previous
; #define LAS __attribute__((address_space(3)))
; __device__ __forceinline__ float bf_lo(unsigned v) { return __uint_as_float(v << 16); }
; __device__ __forceinline__ float bf_hi(unsigned v) { return __uint_as_float(v & 0xffff0000u); }
; __device__ __forceinline__ int lane_id() { int l; asm volatile("v_mbcnt_lo_u32_b32 %0, -1, 0\n\tv_mbcnt_hi_u32_b32 %0, -1, %0\n\ts_nop 1" : "=v"(l)); return l; }
; __device__ __forceinline__ void attn_query8(const unsigned char* __restrict__ KV8, const bf16_t* __restrict__ Z, const int* __restrict__ SEL, bf16_t* __restrict__ YMIX, int t, LAS float* sbuf  ) {
;     const int lane = lane_id(), hd = lane >> 3;
;     const int nsel = (t + 1 < 256) ? (t + 1) : 256, nb = (nsel + 7) >> 3;
;     int iv[4];
; #pragma unroll
;     for (int jj = 0; jj < 4; ++jj) { const int e = lane + 64 * jj; iv[jj] = (e < nsel) ? SEL[(size_t)t * 256 + e] : 0; }
;     f32x2v qf[8];
;     { const u32x4* qp = (const u32x4*)(Z + (size_t)t * ZLD + OFF_Q + lane * 16); const u32x4 a = qp[0], b = qp[1];
;       qf[0] = (f32x2v){bf_lo(a.x), bf_hi(a.x)}; qf[1] = (f32x2v){bf_lo(a.y), bf_hi(a.y)}; qf[2] = (f32x2v){bf_lo(a.z), bf_hi(a.z)}; qf[3] = (f32x2v){bf_lo(a.w), bf_hi(a.w)};
;       qf[4] = (f32x2v){bf_lo(b.x), bf_hi(b.x)}; qf[5] = (f32x2v){bf_lo(b.y), bf_hi(b.y)}; qf[6] = (f32x2v){bf_lo(b.z), bf_hi(b.z)}; qf[7] = (f32x2v){bf_lo(b.w), bf_hi(b.w)}; }
;     const __amdgpu_buffer_rsrc_t rs = __builtin_amdgcn_make_buffer_rsrc((void*)KV8, 0, 0x7fffffff, 0x00020000);
;     const int lvo = lane * 16;
;     LAS float* srow = sbuf + hd * 256;
.LBB0_1247:
	v_readlane_b32 s4, v248, 4
	v_readlane_b32 s5, v248, 5
	s_andn2_b64 vcc, exec, s[4:5]
	s_waitcnt vmcnt(0) lgkmcnt(0)
	s_barrier
	s_cbranch_vccnz .LBB0_1377
	s_mul_i32 s0, s81, 0x800
	s_and_b32 s5, s2, 7
	s_lshr_b32 s8, s2, 3
	s_lshl_b32 s8, s8, 3
	s_add_i32 s80, s8, s81
	s_lshl_b32 s8, s5, 22
	s_add_u32 s16, s60, 0x1b800000
	s_addc_u32 s17, s61, 0
	s_add_u32 s16, s16, s8
	s_addc_u32 s17, s17, 0
	s_and_b32 s17, s17, 0xffff
	s_mov_b32 s18, 0x400000
	s_mov_b32 s19, 0x20000
	s_mov_b32 s26, 0
	s_movk_i32 s27, 0x80
	s_mov_b32 s28, 0x3fb8aa3b
	v_and_b32_e32 v132, 7, v144
	v_lshlrev_b32_e32 v138, 4, v132
	v_lshrrev_b32_e32 v145, 3, v144
	v_lshl_add_u32 v139, v145, 7, s0
	v_lshl_add_u32 v148, v132, 7, s0
	v_lshl_add_u32 v148, v145, 2, v148
	v_xor_b32_e32 v140, 16, v144
	v_lshlrev_b32_e32 v140, 2, v140
	v_xor_b32_e32 v141, 32, v144
	v_lshlrev_b32_e32 v141, 2, v141
	v_mov_b32_e32 v142, 0xff800000
	v_lshlrev_b32_e32 v147, 2, v144
	s_lshl_b32 s8, s5, 8
	v_lshl_add_u32 v146, v132, 5, s8
	v_bfe_u32 v238, v144, 3, 1
	v_lshl_add_u32 v238, v238, 4, v146
	s_min_i32 s8, s80, 0xff
	s_add_i32 s8, s8, 1
	s_lshl_b32 s10, s80, 10
	s_add_u32 s10, s1, s10
	s_addc_u32 s11, s73, 0
	s_cmpk_eq_i32 s8, 0x100
	s_cbranch_scc1 .Latt_full_1
	v_mov_b32_e32 v240, 0
	v_add_u32_e32 v133, 0, v144
	v_cmp_gt_i32_e32 vcc, s8, v133
	s_and_saveexec_b64 s[12:13], vcc
	global_load_dword v240, v147, s[10:11] offset:0
	s_mov_b64 exec, s[12:13]
	v_mov_b32_e32 v241, 0
	v_add_u32_e32 v133, 64, v144
	v_cmp_gt_i32_e32 vcc, s8, v133
	s_and_saveexec_b64 s[12:13], vcc
	global_load_dword v241, v147, s[10:11] offset:256
	s_mov_b64 exec, s[12:13]
	v_mov_b32_e32 v242, 0
	v_add_u32_e32 v133, 128, v144
	v_cmp_gt_i32_e32 vcc, s8, v133
	s_and_saveexec_b64 s[12:13], vcc
	global_load_dword v242, v147, s[10:11] offset:512
	s_mov_b64 exec, s[12:13]
	v_mov_b32_e32 v243, 0
	v_add_u32_e32 v133, 192, v144
	v_cmp_gt_i32_e32 vcc, s8, v133
	s_and_saveexec_b64 s[12:13], vcc
	global_load_dword v243, v147, s[10:11] offset:768
	s_mov_b64 exec, s[12:13]
	s_branch .Latt_idx_1
.Latt_full_1:
	global_load_dword v240, v147, s[10:11] offset:0
	global_load_dword v241, v147, s[10:11] offset:256
	global_load_dword v242, v147, s[10:11] offset:512
	global_load_dword v243, v147, s[10:11] offset:768
; #define LAS __attribute__((address_space(3)))
; __device__ __forceinline__ float bf_lo(unsigned v) { return __uint_as_float(v << 16); }
; __device__ __forceinline__ float bf_hi(unsigned v) { return __uint_as_float(v & 0xffff0000u); }
; __device__ __forceinline__ void attn_query8(const unsigned char* __restrict__ KV8, const bf16_t* __restrict__ Z, const int* __restrict__ SEL, bf16_t* __restrict__ YMIX, int t, LAS float* sbuf  ) {
;     ...
;     const int nsel = (t + 1 < 256) ? (t + 1) : 256, nb = (nsel + 7) >> 3;
;     int iv[4];
; #pragma unroll
;     for (int jj = 0; jj < 4; ++jj) { const int e = lane + 64 * jj; iv[jj] = (e < nsel) ? SEL[(size_t)t * 256 + e] : 0; }
;     f32x2v qf[8];
;     { const u32x4* qp = (const u32x4*)(Z + (size_t)t * ZLD + OFF_Q + lane * 16); const u32x4 a = qp[0], b = qp[1];
;       qf[0] = (f32x2v){bf_lo(a.x), bf_hi(a.x)}; qf[1] = (f32x2v){bf_lo(a.y), bf_hi(a.y)}; qf[2] = (f32x2v){bf_lo(a.z), bf_hi(a.z)}; qf[3] = (f32x2v){bf_lo(a.w), bf_hi(a.w)};
;       qf[4] = (f32x2v){bf_lo(b.x), bf_hi(b.x)}; qf[5] = (f32x2v){bf_lo(b.y), bf_hi(b.y)}; qf[6] = (f32x2v){bf_lo(b.z), bf_hi(b.z)}; qf[7] = (f32x2v){bf_lo(b.w), bf_hi(b.w)}; }
;     const __amdgpu_buffer_rsrc_t rs = __builtin_amdgcn_make_buffer_rsrc((void*)KV8, 0, 0x7fffffff, 0x00020000);
;     const int lvo = lane * 16;
;     LAS float* srow = sbuf + hd * 256;
;     u32x4 A[8], B[8], C[8];
;     const int lb = nb - 1;
;     ...
;     kv8_issue(A, rs, lvo, 0, iv, 0);
;     kv8_issue(B, rs, lvo, 0, iv, CLAMPB(1));
; #pragma unroll 1
;     for (int b = 0; b < nb; b += 3) {
;         kv8_issue(C, rs, lvo, 0, iv, CLAMPB(b + 2));
.Latt_idx_1:
	s_mul_i32 s10, s80, 0x2a00
	s_mul_hi_i32 s11, s80, 0x2a00
	s_add_u32 s10, s42, s10
	s_addc_u32 s11, s43, s11
	global_load_dwordx4 v[244:247], v146, s[10:11] offset:2048
	global_load_dwordx4 v[230:233], v146, s[10:11] offset:2064
	s_waitcnt vmcnt(0)
	ds_write_b32 v148, v240 offset:0
	ds_write_b32 v148, v241 offset:32
	ds_write_b32 v148, v242 offset:64
	ds_write_b32 v148, v243 offset:96
	s_waitcnt lgkmcnt(0)
	ds_read_b128 v[150:153], v139 offset:0
	ds_read_b128 v[154:157], v139 offset:16
	ds_read_b128 v[158:161], v139 offset:32
	ds_read_b128 v[162:165], v139 offset:48
	ds_read_b128 v[166:169], v139 offset:64
	ds_read_b128 v[170:173], v139 offset:80
	ds_read_b128 v[174:177], v139 offset:96
	ds_read_b128 v[178:181], v139 offset:112
	s_waitcnt lgkmcnt(0)
	v_lshl_add_u32 v150, v150, 8, v138
	v_lshl_add_u32 v151, v151, 8, v138
	v_lshl_add_u32 v152, v152, 8, v138
	v_lshl_add_u32 v153, v153, 8, v138
	v_lshl_add_u32 v154, v154, 8, v138
	v_lshl_add_u32 v155, v155, 8, v138
	v_lshl_add_u32 v156, v156, 8, v138
	v_lshl_add_u32 v157, v157, 8, v138
	v_lshl_add_u32 v158, v158, 8, v138
	v_lshl_add_u32 v159, v159, 8, v138
	v_lshl_add_u32 v160, v160, 8, v138
	v_lshl_add_u32 v161, v161, 8, v138
	v_lshl_add_u32 v162, v162, 8, v138
	v_lshl_add_u32 v163, v163, 8, v138
	v_lshl_add_u32 v164, v164, 8, v138
	v_lshl_add_u32 v165, v165, 8, v138
	v_lshl_add_u32 v166, v166, 8, v138
	v_lshl_add_u32 v167, v167, 8, v138
	v_lshl_add_u32 v168, v168, 8, v138
	v_lshl_add_u32 v169, v169, 8, v138
	v_lshl_add_u32 v170, v170, 8, v138
	v_lshl_add_u32 v171, v171, 8, v138
	v_lshl_add_u32 v172, v172, 8, v138
	v_lshl_add_u32 v173, v173, 8, v138
	v_lshl_add_u32 v174, v174, 8, v138
	v_lshl_add_u32 v175, v175, 8, v138
	v_lshl_add_u32 v176, v176, 8, v138
	v_lshl_add_u32 v177, v177, 8, v138
	v_lshl_add_u32 v178, v178, 8, v138
	v_lshl_add_u32 v179, v179, 8, v138
	v_lshl_add_u32 v180, v180, 8, v138
	v_lshl_add_u32 v181, v181, 8, v138
	buffer_load_dwordx4 v[0:3], v150, s[16:19], s26 offen sc0
	buffer_load_dwordx4 v[4:7], v151, s[16:19], s26 offen sc0
	buffer_load_dwordx4 v[8:11], v152, s[16:19], s26 offen sc0
	buffer_load_dwordx4 v[12:15], v153, s[16:19], s26 offen sc0
	buffer_load_dwordx4 v[16:19], v154, s[16:19], s26 offen sc0
	buffer_load_dwordx4 v[20:23], v155, s[16:19], s26 offen sc0
	buffer_load_dwordx4 v[24:27], v156, s[16:19], s26 offen sc0
	buffer_load_dwordx4 v[28:31], v157, s[16:19], s26 offen sc0
	buffer_load_dwordx4 v[32:35], v158, s[16:19], s26 offen sc0
	buffer_load_dwordx4 v[36:39], v159, s[16:19], s26 offen sc0
	buffer_load_dwordx4 v[40:43], v160, s[16:19], s26 offen sc0
	buffer_load_dwordx4 v[44:47], v161, s[16:19], s26 offen sc0
	buffer_load_dwordx4 v[48:51], v162, s[16:19], s26 offen sc0
	buffer_load_dwordx4 v[52:55], v163, s[16:19], s26 offen sc0
	buffer_load_dwordx4 v[56:59], v164, s[16:19], s26 offen sc0
	buffer_load_dwordx4 v[60:63], v165, s[16:19], s26 offen sc0
	buffer_load_dwordx4 v[64:67], v166, s[16:19], s26 offen sc0
	buffer_load_dwordx4 v[68:71], v167, s[16:19], s26 offen sc0
	buffer_load_dwordx4 v[72:75], v168, s[16:19], s26 offen sc0
	buffer_load_dwordx4 v[76:79], v169, s[16:19], s26 offen sc0
	buffer_load_dwordx4 v[80:83], v170, s[16:19], s26 offen sc0
	buffer_load_dwordx4 v[84:87], v171, s[16:19], s26 offen sc0
	buffer_load_dwordx4 v[88:91], v172, s[16:19], s26 offen sc0
	buffer_load_dwordx4 v[92:95], v173, s[16:19], s26 offen sc0
	buffer_load_dwordx4 v[96:99], v174, s[16:19], s26 offen sc0
	buffer_load_dwordx4 v[100:103], v175, s[16:19], s26 offen sc0
	buffer_load_dwordx4 v[104:107], v176, s[16:19], s26 offen sc0
	buffer_load_dwordx4 v[108:111], v177, s[16:19], s26 offen sc0
	buffer_load_dwordx4 v[112:115], v178, s[16:19], s26 offen sc0
	buffer_load_dwordx4 v[116:119], v179, s[16:19], s26 offen sc0
	buffer_load_dwordx4 v[120:123], v180, s[16:19], s26 offen sc0
	buffer_load_dwordx4 v[124:127], v181, s[16:19], s26 offen sc0
.Latt_unit:
	s_min_i32 s4, s80, 0xff
	s_add_i32 s4, s4, 1
	v_sub_u32_e32 v143, s4, v145
	s_waitcnt vmcnt(32)
	v_lshlrev_b32_e32 v182, 16, v244
	v_and_b32_e32 v183, 0xffff0000, v244
	v_lshlrev_b32_e32 v184, 16, v245
	v_and_b32_e32 v185, 0xffff0000, v245
	v_lshlrev_b32_e32 v186, 16, v246
	v_and_b32_e32 v187, 0xffff0000, v246
	v_lshlrev_b32_e32 v188, 16, v247
	v_and_b32_e32 v189, 0xffff0000, v247
	v_lshlrev_b32_e32 v190, 16, v230
	v_and_b32_e32 v191, 0xffff0000, v230
	v_lshlrev_b32_e32 v192, 16, v231
	v_and_b32_e32 v193, 0xffff0000, v231
	v_lshlrev_b32_e32 v194, 16, v232
	v_and_b32_e32 v195, 0xffff0000, v232
	v_lshlrev_b32_e32 v196, 16, v233
	v_and_b32_e32 v197, 0xffff0000, v233
	s_add_i32 s6, s80, 0x100
	s_min_i32 s6, s6, 0x3fff
	s_min_i32 s8, s6, 0xff
	s_add_i32 s8, s8, 1
	s_lshl_b32 s10, s6, 10
	s_add_u32 s10, s1, s10
	s_addc_u32 s11, s73, 0
	s_cmpk_eq_i32 s8, 0x100
	s_cbranch_scc1 .Latt_full_2
	v_mov_b32_e32 v240, 0
	v_add_u32_e32 v133, 0, v144
	v_cmp_gt_i32_e32 vcc, s8, v133
	s_and_saveexec_b64 s[12:13], vcc
	global_load_dword v240, v147, s[10:11] offset:0
	s_mov_b64 exec, s[12:13]
	v_mov_b32_e32 v241, 0
	v_add_u32_e32 v133, 64, v144
	v_cmp_gt_i32_e32 vcc, s8, v133
	s_and_saveexec_b64 s[12:13], vcc
	global_load_dword v241, v147, s[10:11] offset:256
	s_mov_b64 exec, s[12:13]
	v_mov_b32_e32 v242, 0
	v_add_u32_e32 v133, 128, v144
	v_cmp_gt_i32_e32 vcc, s8, v133
	s_and_saveexec_b64 s[12:13], vcc
	global_load_dword v242, v147, s[10:11] offset:512
	s_mov_b64 exec, s[12:13]
	v_mov_b32_e32 v243, 0
	v_add_u32_e32 v133, 192, v144
	v_cmp_gt_i32_e32 vcc, s8, v133
	s_and_saveexec_b64 s[12:13], vcc
	global_load_dword v243, v147, s[10:11] offset:768
	s_mov_b64 exec, s[12:13]
	s_branch .Latt_idx_2

; #define LAS __attribute__((address_space(3)))
; __device__ __forceinline__ float red8(float v) { v += dpp_f<0xB1>(v); v += dpp_f<0x4E>(v); v += dpp_f<0x141>(v); return v; }
; __device__ __forceinline__ void kv8_qk(const u32x4 (&buf)[8], const f32x2v (&q2)[8], LAS float* srow, int b, int lane) {
; #pragma unroll
;     for (int u = 0; u < 8; ++u) {
;         const u32x4 k = buf[u];
;         f32x2v s0 = q2[0] * __builtin_amdgcn_cvt_pk_f32_fp8(k.x, false), s1 = q2[1] * __builtin_amdgcn_cvt_pk_f32_fp8(k.x, true);
;         s0 = __builtin_elementwise_fma(q2[2], __builtin_amdgcn_cvt_pk_f32_fp8(k.y, false), s0); s1 = __builtin_elementwise_fma(q2[3], __builtin_amdgcn_cvt_pk_f32_fp8(k.y, true), s1);
;         s0 = __builtin_elementwise_fma(q2[4], __builtin_amdgcn_cvt_pk_f32_fp8(k.z, false), s0); s1 = __builtin_elementwise_fma(q2[5], __builtin_amdgcn_cvt_pk_f32_fp8(k.z, true), s1);
;         s0 = __builtin_elementwise_fma(q2[6], __builtin_amdgcn_cvt_pk_f32_fp8(k.w, false), s0); s1 = __builtin_elementwise_fma(q2[7], __builtin_amdgcn_cvt_pk_f32_fp8(k.w, true), s1);
;         const f32x2v t = s0 + s1;
;         const float s = red8(t.x + t.y);
;         if ((lane & 7) == 0) srow[b * 8 + u] = s;
;     }
; }
.Latt_idx_2:
	s_mul_i32 s10, s6, 0x2a00
	s_mul_hi_i32 s11, s6, 0x2a00
	s_add_u32 s10, s42, s10
	s_addc_u32 s11, s43, s11
	global_load_dwordx4 v[244:247], v146, s[10:11] offset:2048
	global_load_dwordx4 v[230:233], v146, s[10:11] offset:2064
	s_waitcnt vmcnt(37)
	v_cvt_pk_f32_fp8_e32 v[214:215], v0
	v_cvt_pk_f32_fp8_sdwa v[216:217], v0 src0_sel:WORD_1
	v_pk_mul_f32 v[128:129], v[214:215], v[182:183]
	v_cvt_pk_f32_fp8_e32 v[218:219], v1
	s_nop 0
	v_pk_fma_f32 v[128:129], v[184:185], v[216:217], v[128:129]
	v_cvt_pk_f32_fp8_sdwa v[220:221], v1 src0_sel:WORD_1
	v_pk_fma_f32 v[128:129], v[186:187], v[218:219], v[128:129]
	v_cvt_pk_f32_fp8_e32 v[222:223], v2
	v_pk_fma_f32 v[128:129], v[188:189], v[220:221], v[128:129]
	v_cvt_pk_f32_fp8_sdwa v[224:225], v2 src0_sel:WORD_1
	s_nop 0
	v_pk_fma_f32 v[128:129], v[190:191], v[222:223], v[128:129]
	v_cvt_pk_f32_fp8_e32 v[226:227], v3
	v_pk_fma_f32 v[128:129], v[192:193], v[224:225], v[128:129]
	v_cvt_pk_f32_fp8_sdwa v[228:229], v3 src0_sel:WORD_1
	v_pk_fma_f32 v[128:129], v[194:195], v[226:227], v[128:129]
	v_pk_fma_f32 v[128:129], v[196:197], v[228:229], v[128:129]
	buffer_load_dwordx4 v[0:3], v150, s[16:19], s27 offen sc0
	s_nop 0
	v_add_f32_e32 v132, v128, v129
	s_waitcnt vmcnt(37)
	v_cvt_pk_f32_fp8_e32 v[214:215], v4
	v_cvt_pk_f32_fp8_sdwa v[216:217], v4 src0_sel:WORD_1
	v_pk_mul_f32 v[128:129], v[214:215], v[182:183]
	v_cvt_pk_f32_fp8_e32 v[218:219], v5
	v_add_f32_dpp v132, v132, v132 quad_perm:[1,0,3,2] row_mask:0xf bank_mask:0xf
	v_pk_fma_f32 v[128:129], v[184:185], v[216:217], v[128:129]
	v_cvt_pk_f32_fp8_sdwa v[220:221], v5 src0_sel:WORD_1
	v_pk_fma_f32 v[128:129], v[186:187], v[218:219], v[128:129]
	v_cvt_pk_f32_fp8_e32 v[222:223], v6
	v_pk_fma_f32 v[128:129], v[188:189], v[220:221], v[128:129]
	v_cvt_pk_f32_fp8_sdwa v[224:225], v6 src0_sel:WORD_1
	v_add_f32_dpp v132, v132, v132 quad_perm:[2,3,0,1] row_mask:0xf bank_mask:0xf
	v_pk_fma_f32 v[128:129], v[190:191], v[222:223], v[128:129]
	v_cvt_pk_f32_fp8_e32 v[226:227], v7
	v_pk_fma_f32 v[128:129], v[192:193], v[224:225], v[128:129]
	v_cvt_pk_f32_fp8_sdwa v[228:229], v7 src0_sel:WORD_1
	v_pk_fma_f32 v[128:129], v[194:195], v[226:227], v[128:129]
	v_pk_fma_f32 v[128:129], v[196:197], v[228:229], v[128:129]
	buffer_load_dwordx4 v[4:7], v151, s[16:19], s27 offen sc0
	v_add_f32_dpp v150, v132, v132 row_half_mirror row_mask:0xf bank_mask:0xf
	v_add_f32_e32 v133, v128, v129
	s_waitcnt vmcnt(37)
	v_cvt_pk_f32_fp8_e32 v[214:215], v8
	v_cvt_pk_f32_fp8_sdwa v[216:217], v8 src0_sel:WORD_1
	v_pk_mul_f32 v[128:129], v[214:215], v[182:183]
	v_cvt_pk_f32_fp8_e32 v[218:219], v9
	v_add_f32_dpp v133, v133, v133 quad_perm:[1,0,3,2] row_mask:0xf bank_mask:0xf
	v_pk_fma_f32 v[128:129], v[184:185], v[216:217], v[128:129]
	v_cvt_pk_f32_fp8_sdwa v[220:221], v9 src0_sel:WORD_1
	v_pk_fma_f32 v[128:129], v[186:187], v[218:219], v[128:129]
	v_cvt_pk_f32_fp8_e32 v[222:223], v10
	v_pk_fma_f32 v[128:129], v[188:189], v[220:221], v[128:129]
	v_cvt_pk_f32_fp8_sdwa v[224:225], v10 src0_sel:WORD_1
	v_add_f32_dpp v133, v133, v133 quad_perm:[2,3,0,1] row_mask:0xf bank_mask:0xf
	v_pk_fma_f32 v[128:129], v[190:191], v[222:223], v[128:129]
	v_cvt_pk_f32_fp8_e32 v[226:227], v11
	v_pk_fma_f32 v[128:129], v[192:193], v[224:225], v[128:129]
	v_cvt_pk_f32_fp8_sdwa v[228:229], v11 src0_sel:WORD_1
	v_pk_fma_f32 v[128:129], v[194:195], v[226:227], v[128:129]
	v_pk_fma_f32 v[128:129], v[196:197], v[228:229], v[128:129]
	buffer_load_dwordx4 v[8:11], v152, s[16:19], s27 offen sc0
	v_add_f32_dpp v151, v133, v133 row_half_mirror row_mask:0xf bank_mask:0xf
	v_add_f32_e32 v132, v128, v129
	s_waitcnt vmcnt(37)
	v_cvt_pk_f32_fp8_e32 v[214:215], v12
	v_cvt_pk_f32_fp8_sdwa v[216:217], v12 src0_sel:WORD_1
	v_pk_mul_f32 v[128:129], v[214:215], v[182:183]
	v_cvt_pk_f32_fp8_e32 v[218:219], v13
	v_add_f32_dpp v132, v132, v132 quad_perm:[1,0,3,2] row_mask:0xf bank_mask:0xf
	v_pk_fma_f32 v[128:129], v[184:185], v[216:217], v[128:129]
	v_cvt_pk_f32_fp8_sdwa v[220:221], v13 src0_sel:WORD_1
	v_pk_fma_f32 v[128:129], v[186:187], v[218:219], v[128:129]
	v_cvt_pk_f32_fp8_e32 v[222:223], v14
	v_pk_fma_f32 v[128:129], v[188:189], v[220:221], v[128:129]
	v_cvt_pk_f32_fp8_sdwa v[224:225], v14 src0_sel:WORD_1
	v_add_f32_dpp v132, v132, v132 quad_perm:[2,3,0,1] row_mask:0xf bank_mask:0xf
	v_pk_fma_f32 v[128:129], v[190:191], v[222:223], v[128:129]
	v_cvt_pk_f32_fp8_e32 v[226:227], v15
	v_pk_fma_f32 v[128:129], v[192:193], v[224:225], v[128:129]
	v_cvt_pk_f32_fp8_sdwa v[228:229], v15 src0_sel:WORD_1
	v_pk_fma_f32 v[128:129], v[194:195], v[226:227], v[128:129]
	v_pk_fma_f32 v[128:129], v[196:197], v[228:229], v[128:129]
	buffer_load_dwordx4 v[12:15], v153, s[16:19], s27 offen sc0
	v_add_f32_dpp v152, v132, v132 row_half_mirror row_mask:0xf bank_mask:0xf
	v_add_f32_e32 v133, v128, v129
	s_waitcnt vmcnt(37)
	v_cvt_pk_f32_fp8_e32 v[214:215], v16
	v_cvt_pk_f32_fp8_sdwa v[216:217], v16 src0_sel:WORD_1
	v_pk_mul_f32 v[128:129], v[214:215], v[182:183]
	v_cvt_pk_f32_fp8_e32 v[218:219], v17
	v_add_f32_dpp v133, v133, v133 quad_perm:[1,0,3,2] row_mask:0xf bank_mask:0xf
	v_pk_fma_f32 v[128:129], v[184:185], v[216:217], v[128:129]
	v_cvt_pk_f32_fp8_sdwa v[220:221], v17 src0_sel:WORD_1
	v_pk_fma_f32 v[128:129], v[186:187], v[218:219], v[128:129]
	v_cvt_pk_f32_fp8_e32 v[222:223], v18
	v_pk_fma_f32 v[128:129], v[188:189], v[220:221], v[128:129]
	v_cvt_pk_f32_fp8_sdwa v[224:225], v18 src0_sel:WORD_1
	v_add_f32_dpp v133, v133, v133 quad_perm:[2,3,0,1] row_mask:0xf bank_mask:0xf
	v_pk_fma_f32 v[128:129], v[190:191], v[222:223], v[128:129]
	v_cvt_pk_f32_fp8_e32 v[226:227], v19
	v_pk_fma_f32 v[128:129], v[192:193], v[224:225], v[128:129]
	v_cvt_pk_f32_fp8_sdwa v[228:229], v19 src0_sel:WORD_1
	v_pk_fma_f32 v[128:129], v[194:195], v[226:227], v[128:129]
	v_pk_fma_f32 v[128:129], v[196:197], v[228:229], v[128:129]
	buffer_load_dwordx4 v[16:19], v154, s[16:19], s27 offen sc0
	v_add_f32_dpp v153, v133, v133 row_half_mirror row_mask:0xf bank_mask:0xf
	v_add_f32_e32 v132, v128, v129
	s_waitcnt vmcnt(37)
; #define LAS __attribute__((address_space(3)))
; __device__ __forceinline__ float red8(float v) { v += dpp_f<0xB1>(v); v += dpp_f<0x4E>(v); v += dpp_f<0x141>(v); return v; }
; __device__ __forceinline__ void kv8_qk(const u32x4 (&buf)[8], const f32x2v (&q2)[8], LAS float* srow, int b, int lane) {
; #pragma unroll
;     for (int u = 0; u < 8; ++u) {
;         const u32x4 k = buf[u];
;         f32x2v s0 = q2[0] * __builtin_amdgcn_cvt_pk_f32_fp8(k.x, false), s1 = q2[1] * __builtin_amdgcn_cvt_pk_f32_fp8(k.x, true);
;         s0 = __builtin_elementwise_fma(q2[2], __builtin_amdgcn_cvt_pk_f32_fp8(k.y, false), s0); s1 = __builtin_elementwise_fma(q2[3], __builtin_amdgcn_cvt_pk_f32_fp8(k.y, true), s1);
;         s0 = __builtin_elementwise_fma(q2[4], __builtin_amdgcn_cvt_pk_f32_fp8(k.z, false), s0); s1 = __builtin_elementwise_fma(q2[5], __builtin_amdgcn_cvt_pk_f32_fp8(k.z, true), s1);
;         s0 = __builtin_elementwise_fma(q2[6], __builtin_amdgcn_cvt_pk_f32_fp8(k.w, false), s0); s1 = __builtin_elementwise_fma(q2[7], __builtin_amdgcn_cvt_pk_f32_fp8(k.w, true), s1);
;         const f32x2v t = s0 + s1;
;         const float s = red8(t.x + t.y);
;         if ((lane & 7) == 0) srow[b * 8 + u] = s;
;     }
; }
	v_cvt_pk_f32_fp8_e32 v[214:215], v20
	v_cvt_pk_f32_fp8_sdwa v[216:217], v20 src0_sel:WORD_1
	v_pk_mul_f32 v[128:129], v[214:215], v[182:183]
	v_cvt_pk_f32_fp8_e32 v[218:219], v21
	v_add_f32_dpp v132, v132, v132 quad_perm:[1,0,3,2] row_mask:0xf bank_mask:0xf
	v_pk_fma_f32 v[128:129], v[184:185], v[216:217], v[128:129]
	v_cvt_pk_f32_fp8_sdwa v[220:221], v21 src0_sel:WORD_1
	v_pk_fma_f32 v[128:129], v[186:187], v[218:219], v[128:129]
	v_cvt_pk_f32_fp8_e32 v[222:223], v22
	v_pk_fma_f32 v[128:129], v[188:189], v[220:221], v[128:129]
	v_cvt_pk_f32_fp8_sdwa v[224:225], v22 src0_sel:WORD_1
	v_add_f32_dpp v132, v132, v132 quad_perm:[2,3,0,1] row_mask:0xf bank_mask:0xf
	v_pk_fma_f32 v[128:129], v[190:191], v[222:223], v[128:129]
	v_cvt_pk_f32_fp8_e32 v[226:227], v23
	v_pk_fma_f32 v[128:129], v[192:193], v[224:225], v[128:129]
	v_cvt_pk_f32_fp8_sdwa v[228:229], v23 src0_sel:WORD_1
	v_pk_fma_f32 v[128:129], v[194:195], v[226:227], v[128:129]
	v_pk_fma_f32 v[128:129], v[196:197], v[228:229], v[128:129]
	buffer_load_dwordx4 v[20:23], v155, s[16:19], s27 offen sc0
	v_add_f32_dpp v154, v132, v132 row_half_mirror row_mask:0xf bank_mask:0xf
	v_add_f32_e32 v133, v128, v129
	s_waitcnt vmcnt(37)
	v_cvt_pk_f32_fp8_e32 v[214:215], v24
	v_cvt_pk_f32_fp8_sdwa v[216:217], v24 src0_sel:WORD_1
	v_pk_mul_f32 v[128:129], v[214:215], v[182:183]
	v_cvt_pk_f32_fp8_e32 v[218:219], v25
	v_add_f32_dpp v133, v133, v133 quad_perm:[1,0,3,2] row_mask:0xf bank_mask:0xf
	v_pk_fma_f32 v[128:129], v[184:185], v[216:217], v[128:129]
	v_cvt_pk_f32_fp8_sdwa v[220:221], v25 src0_sel:WORD_1
	v_pk_fma_f32 v[128:129], v[186:187], v[218:219], v[128:129]
	v_cvt_pk_f32_fp8_e32 v[222:223], v26
	v_pk_fma_f32 v[128:129], v[188:189], v[220:221], v[128:129]
	v_cvt_pk_f32_fp8_sdwa v[224:225], v26 src0_sel:WORD_1
	v_add_f32_dpp v133, v133, v133 quad_perm:[2,3,0,1] row_mask:0xf bank_mask:0xf
	v_pk_fma_f32 v[128:129], v[190:191], v[222:223], v[128:129]
	v_cvt_pk_f32_fp8_e32 v[226:227], v27
	v_pk_fma_f32 v[128:129], v[192:193], v[224:225], v[128:129]
	v_cvt_pk_f32_fp8_sdwa v[228:229], v27 src0_sel:WORD_1
	v_pk_fma_f32 v[128:129], v[194:195], v[226:227], v[128:129]
	v_pk_fma_f32 v[128:129], v[196:197], v[228:229], v[128:129]
	buffer_load_dwordx4 v[24:27], v156, s[16:19], s27 offen sc0
	v_add_f32_dpp v155, v133, v133 row_half_mirror row_mask:0xf bank_mask:0xf
	v_add_f32_e32 v132, v128, v129
	s_waitcnt vmcnt(37)
	v_cvt_pk_f32_fp8_e32 v[214:215], v28
	v_cvt_pk_f32_fp8_sdwa v[216:217], v28 src0_sel:WORD_1
	v_pk_mul_f32 v[128:129], v[214:215], v[182:183]
	v_cvt_pk_f32_fp8_e32 v[218:219], v29
	v_add_f32_dpp v132, v132, v132 quad_perm:[1,0,3,2] row_mask:0xf bank_mask:0xf
	v_pk_fma_f32 v[128:129], v[184:185], v[216:217], v[128:129]
	v_cvt_pk_f32_fp8_sdwa v[220:221], v29 src0_sel:WORD_1
	v_pk_fma_f32 v[128:129], v[186:187], v[218:219], v[128:129]
	v_cvt_pk_f32_fp8_e32 v[222:223], v30
	v_pk_fma_f32 v[128:129], v[188:189], v[220:221], v[128:129]
	v_cvt_pk_f32_fp8_sdwa v[224:225], v30 src0_sel:WORD_1
	v_add_f32_dpp v132, v132, v132 quad_perm:[2,3,0,1] row_mask:0xf bank_mask:0xf
	v_pk_fma_f32 v[128:129], v[190:191], v[222:223], v[128:129]
	v_cvt_pk_f32_fp8_e32 v[226:227], v31
	v_pk_fma_f32 v[128:129], v[192:193], v[224:225], v[128:129]
	v_cvt_pk_f32_fp8_sdwa v[228:229], v31 src0_sel:WORD_1
	v_pk_fma_f32 v[128:129], v[194:195], v[226:227], v[128:129]
	v_pk_fma_f32 v[128:129], v[196:197], v[228:229], v[128:129]
	buffer_load_dwordx4 v[28:31], v157, s[16:19], s27 offen sc0
	v_add_f32_dpp v156, v132, v132 row_half_mirror row_mask:0xf bank_mask:0xf
	v_add_f32_e32 v133, v128, v129
	s_waitcnt vmcnt(37)
	v_cvt_pk_f32_fp8_e32 v[214:215], v32
	v_cvt_pk_f32_fp8_sdwa v[216:217], v32 src0_sel:WORD_1
	v_pk_mul_f32 v[128:129], v[214:215], v[182:183]
	v_cvt_pk_f32_fp8_e32 v[218:219], v33
	v_add_f32_dpp v133, v133, v133 quad_perm:[1,0,3,2] row_mask:0xf bank_mask:0xf
	v_pk_fma_f32 v[128:129], v[184:185], v[216:217], v[128:129]
	v_cvt_pk_f32_fp8_sdwa v[220:221], v33 src0_sel:WORD_1
	v_pk_fma_f32 v[128:129], v[186:187], v[218:219], v[128:129]
	v_cvt_pk_f32_fp8_e32 v[222:223], v34
	v_pk_fma_f32 v[128:129], v[188:189], v[220:221], v[128:129]
	v_cvt_pk_f32_fp8_sdwa v[224:225], v34 src0_sel:WORD_1
	v_add_f32_dpp v133, v133, v133 quad_perm:[2,3,0,1] row_mask:0xf bank_mask:0xf
	v_pk_fma_f32 v[128:129], v[190:191], v[222:223], v[128:129]
	v_cvt_pk_f32_fp8_e32 v[226:227], v35
	v_pk_fma_f32 v[128:129], v[192:193], v[224:225], v[128:129]
	v_cvt_pk_f32_fp8_sdwa v[228:229], v35 src0_sel:WORD_1
	v_pk_fma_f32 v[128:129], v[194:195], v[226:227], v[128:129]
	v_pk_fma_f32 v[128:129], v[196:197], v[228:229], v[128:129]
	buffer_load_dwordx4 v[32:35], v158, s[16:19], s27 offen sc0
	v_add_f32_dpp v157, v133, v133 row_half_mirror row_mask:0xf bank_mask:0xf
	v_add_f32_e32 v132, v128, v129
	s_waitcnt vmcnt(37)
	v_cvt_pk_f32_fp8_e32 v[214:215], v36
	v_cvt_pk_f32_fp8_sdwa v[216:217], v36 src0_sel:WORD_1
	v_pk_mul_f32 v[128:129], v[214:215], v[182:183]
	v_cvt_pk_f32_fp8_e32 v[218:219], v37
	v_add_f32_dpp v132, v132, v132 quad_perm:[1,0,3,2] row_mask:0xf bank_mask:0xf
	v_pk_fma_f32 v[128:129], v[184:185], v[216:217], v[128:129]
	v_cvt_pk_f32_fp8_sdwa v[220:221], v37 src0_sel:WORD_1
	v_pk_fma_f32 v[128:129], v[186:187], v[218:219], v[128:129]
	v_cvt_pk_f32_fp8_e32 v[222:223], v38
	v_pk_fma_f32 v[128:129], v[188:189], v[220:221], v[128:129]
	v_cvt_pk_f32_fp8_sdwa v[224:225], v38 src0_sel:WORD_1
	v_add_f32_dpp v132, v132, v132 quad_perm:[2,3,0,1] row_mask:0xf bank_mask:0xf
	v_pk_fma_f32 v[128:129], v[190:191], v[222:223], v[128:129]
	v_cvt_pk_f32_fp8_e32 v[226:227], v39
	v_pk_fma_f32 v[128:129], v[192:193], v[224:225], v[128:129]
	v_cvt_pk_f32_fp8_sdwa v[228:229], v39 src0_sel:WORD_1
	v_pk_fma_f32 v[128:129], v[194:195], v[226:227], v[128:129]
	v_pk_fma_f32 v[128:129], v[196:197], v[228:229], v[128:129]
	buffer_load_dwordx4 v[36:39], v159, s[16:19], s27 offen sc0
	v_add_f32_dpp v158, v132, v132 row_half_mirror row_mask:0xf bank_mask:0xf
	v_add_f32_e32 v133, v128, v129
	s_waitcnt vmcnt(37)
; #define LAS __attribute__((address_space(3)))
; __device__ __forceinline__ float red8(float v) { v += dpp_f<0xB1>(v); v += dpp_f<0x4E>(v); v += dpp_f<0x141>(v); return v; }
; __device__ __forceinline__ void kv8_qk(const u32x4 (&buf)[8], const f32x2v (&q2)[8], LAS float* srow, int b, int lane) {
; #pragma unroll
;     for (int u = 0; u < 8; ++u) {
;         const u32x4 k = buf[u];
;         f32x2v s0 = q2[0] * __builtin_amdgcn_cvt_pk_f32_fp8(k.x, false), s1 = q2[1] * __builtin_amdgcn_cvt_pk_f32_fp8(k.x, true);
;         s0 = __builtin_elementwise_fma(q2[2], __builtin_amdgcn_cvt_pk_f32_fp8(k.y, false), s0); s1 = __builtin_elementwise_fma(q2[3], __builtin_amdgcn_cvt_pk_f32_fp8(k.y, true), s1);
;         s0 = __builtin_elementwise_fma(q2[4], __builtin_amdgcn_cvt_pk_f32_fp8(k.z, false), s0); s1 = __builtin_elementwise_fma(q2[5], __builtin_amdgcn_cvt_pk_f32_fp8(k.z, true), s1);
;         s0 = __builtin_elementwise_fma(q2[6], __builtin_amdgcn_cvt_pk_f32_fp8(k.w, false), s0); s1 = __builtin_elementwise_fma(q2[7], __builtin_amdgcn_cvt_pk_f32_fp8(k.w, true), s1);
;         const f32x2v t = s0 + s1;
;         const float s = red8(t.x + t.y);
;         if ((lane & 7) == 0) srow[b * 8 + u] = s;
;     }
; }
	v_cvt_pk_f32_fp8_e32 v[214:215], v40
	v_cvt_pk_f32_fp8_sdwa v[216:217], v40 src0_sel:WORD_1
	v_pk_mul_f32 v[128:129], v[214:215], v[182:183]
	v_cvt_pk_f32_fp8_e32 v[218:219], v41
	v_add_f32_dpp v133, v133, v133 quad_perm:[1,0,3,2] row_mask:0xf bank_mask:0xf
	v_pk_fma_f32 v[128:129], v[184:185], v[216:217], v[128:129]
	v_cvt_pk_f32_fp8_sdwa v[220:221], v41 src0_sel:WORD_1
	v_pk_fma_f32 v[128:129], v[186:187], v[218:219], v[128:129]
	v_cvt_pk_f32_fp8_e32 v[222:223], v42
	v_pk_fma_f32 v[128:129], v[188:189], v[220:221], v[128:129]
	v_cvt_pk_f32_fp8_sdwa v[224:225], v42 src0_sel:WORD_1
	v_add_f32_dpp v133, v133, v133 quad_perm:[2,3,0,1] row_mask:0xf bank_mask:0xf
	v_pk_fma_f32 v[128:129], v[190:191], v[222:223], v[128:129]
	v_cvt_pk_f32_fp8_e32 v[226:227], v43
	v_pk_fma_f32 v[128:129], v[192:193], v[224:225], v[128:129]
	v_cvt_pk_f32_fp8_sdwa v[228:229], v43 src0_sel:WORD_1
	v_pk_fma_f32 v[128:129], v[194:195], v[226:227], v[128:129]
	v_pk_fma_f32 v[128:129], v[196:197], v[228:229], v[128:129]
	buffer_load_dwordx4 v[40:43], v160, s[16:19], s27 offen sc0
	v_add_f32_dpp v159, v133, v133 row_half_mirror row_mask:0xf bank_mask:0xf
	v_add_f32_e32 v132, v128, v129
	s_waitcnt vmcnt(37)
	v_cvt_pk_f32_fp8_e32 v[214:215], v44
	v_cvt_pk_f32_fp8_sdwa v[216:217], v44 src0_sel:WORD_1
	v_pk_mul_f32 v[128:129], v[214:215], v[182:183]
	v_cvt_pk_f32_fp8_e32 v[218:219], v45
	v_add_f32_dpp v132, v132, v132 quad_perm:[1,0,3,2] row_mask:0xf bank_mask:0xf
	v_pk_fma_f32 v[128:129], v[184:185], v[216:217], v[128:129]
	v_cvt_pk_f32_fp8_sdwa v[220:221], v45 src0_sel:WORD_1
	v_pk_fma_f32 v[128:129], v[186:187], v[218:219], v[128:129]
	v_cvt_pk_f32_fp8_e32 v[222:223], v46
	v_pk_fma_f32 v[128:129], v[188:189], v[220:221], v[128:129]
	v_cvt_pk_f32_fp8_sdwa v[224:225], v46 src0_sel:WORD_1
	v_add_f32_dpp v132, v132, v132 quad_perm:[2,3,0,1] row_mask:0xf bank_mask:0xf
	v_pk_fma_f32 v[128:129], v[190:191], v[222:223], v[128:129]
	v_cvt_pk_f32_fp8_e32 v[226:227], v47
	v_pk_fma_f32 v[128:129], v[192:193], v[224:225], v[128:129]
	v_cvt_pk_f32_fp8_sdwa v[228:229], v47 src0_sel:WORD_1
	v_pk_fma_f32 v[128:129], v[194:195], v[226:227], v[128:129]
	v_pk_fma_f32 v[128:129], v[196:197], v[228:229], v[128:129]
	buffer_load_dwordx4 v[44:47], v161, s[16:19], s27 offen sc0
	v_add_f32_dpp v160, v132, v132 row_half_mirror row_mask:0xf bank_mask:0xf
	v_add_f32_e32 v133, v128, v129
	s_waitcnt vmcnt(37)
	v_cvt_pk_f32_fp8_e32 v[214:215], v48
	v_cvt_pk_f32_fp8_sdwa v[216:217], v48 src0_sel:WORD_1
	v_pk_mul_f32 v[128:129], v[214:215], v[182:183]
	v_cvt_pk_f32_fp8_e32 v[218:219], v49
	v_add_f32_dpp v133, v133, v133 quad_perm:[1,0,3,2] row_mask:0xf bank_mask:0xf
	v_pk_fma_f32 v[128:129], v[184:185], v[216:217], v[128:129]
	v_cvt_pk_f32_fp8_sdwa v[220:221], v49 src0_sel:WORD_1
	v_pk_fma_f32 v[128:129], v[186:187], v[218:219], v[128:129]
	v_cvt_pk_f32_fp8_e32 v[222:223], v50
	v_pk_fma_f32 v[128:129], v[188:189], v[220:221], v[128:129]
	v_cvt_pk_f32_fp8_sdwa v[224:225], v50 src0_sel:WORD_1
	v_add_f32_dpp v133, v133, v133 quad_perm:[2,3,0,1] row_mask:0xf bank_mask:0xf
	v_pk_fma_f32 v[128:129], v[190:191], v[222:223], v[128:129]
	v_cvt_pk_f32_fp8_e32 v[226:227], v51
	v_pk_fma_f32 v[128:129], v[192:193], v[224:225], v[128:129]
	v_cvt_pk_f32_fp8_sdwa v[228:229], v51 src0_sel:WORD_1
	v_pk_fma_f32 v[128:129], v[194:195], v[226:227], v[128:129]
	v_pk_fma_f32 v[128:129], v[196:197], v[228:229], v[128:129]
	buffer_load_dwordx4 v[48:51], v162, s[16:19], s27 offen sc0
	v_add_f32_dpp v161, v133, v133 row_half_mirror row_mask:0xf bank_mask:0xf
	v_add_f32_e32 v132, v128, v129
	s_waitcnt vmcnt(37)
	v_cvt_pk_f32_fp8_e32 v[214:215], v52
	v_cvt_pk_f32_fp8_sdwa v[216:217], v52 src0_sel:WORD_1
	v_pk_mul_f32 v[128:129], v[214:215], v[182:183]
	v_cvt_pk_f32_fp8_e32 v[218:219], v53
	v_add_f32_dpp v132, v132, v132 quad_perm:[1,0,3,2] row_mask:0xf bank_mask:0xf
	v_pk_fma_f32 v[128:129], v[184:185], v[216:217], v[128:129]
	v_cvt_pk_f32_fp8_sdwa v[220:221], v53 src0_sel:WORD_1
	v_pk_fma_f32 v[128:129], v[186:187], v[218:219], v[128:129]
	v_cvt_pk_f32_fp8_e32 v[222:223], v54
	v_pk_fma_f32 v[128:129], v[188:189], v[220:221], v[128:129]
	v_cvt_pk_f32_fp8_sdwa v[224:225], v54 src0_sel:WORD_1
	v_add_f32_dpp v132, v132, v132 quad_perm:[2,3,0,1] row_mask:0xf bank_mask:0xf
	v_pk_fma_f32 v[128:129], v[190:191], v[222:223], v[128:129]
	v_cvt_pk_f32_fp8_e32 v[226:227], v55
	v_pk_fma_f32 v[128:129], v[192:193], v[224:225], v[128:129]
	v_cvt_pk_f32_fp8_sdwa v[228:229], v55 src0_sel:WORD_1
	v_pk_fma_f32 v[128:129], v[194:195], v[226:227], v[128:129]
	v_pk_fma_f32 v[128:129], v[196:197], v[228:229], v[128:129]
	buffer_load_dwordx4 v[52:55], v163, s[16:19], s27 offen sc0
	v_add_f32_dpp v162, v132, v132 row_half_mirror row_mask:0xf bank_mask:0xf
	v_add_f32_e32 v133, v128, v129
	s_waitcnt vmcnt(37)
	v_cvt_pk_f32_fp8_e32 v[214:215], v56
	v_cvt_pk_f32_fp8_sdwa v[216:217], v56 src0_sel:WORD_1
	v_pk_mul_f32 v[128:129], v[214:215], v[182:183]
	v_cvt_pk_f32_fp8_e32 v[218:219], v57
	v_add_f32_dpp v133, v133, v133 quad_perm:[1,0,3,2] row_mask:0xf bank_mask:0xf
	v_pk_fma_f32 v[128:129], v[184:185], v[216:217], v[128:129]
	v_cvt_pk_f32_fp8_sdwa v[220:221], v57 src0_sel:WORD_1
	v_pk_fma_f32 v[128:129], v[186:187], v[218:219], v[128:129]
	v_cvt_pk_f32_fp8_e32 v[222:223], v58
	v_pk_fma_f32 v[128:129], v[188:189], v[220:221], v[128:129]
	v_cvt_pk_f32_fp8_sdwa v[224:225], v58 src0_sel:WORD_1
	v_add_f32_dpp v133, v133, v133 quad_perm:[2,3,0,1] row_mask:0xf bank_mask:0xf
	v_pk_fma_f32 v[128:129], v[190:191], v[222:223], v[128:129]
	v_cvt_pk_f32_fp8_e32 v[226:227], v59
	v_pk_fma_f32 v[128:129], v[192:193], v[224:225], v[128:129]
	v_cvt_pk_f32_fp8_sdwa v[228:229], v59 src0_sel:WORD_1
	v_pk_fma_f32 v[128:129], v[194:195], v[226:227], v[128:129]
	v_pk_fma_f32 v[128:129], v[196:197], v[228:229], v[128:129]
	buffer_load_dwordx4 v[56:59], v164, s[16:19], s27 offen sc0
	v_add_f32_dpp v163, v133, v133 row_half_mirror row_mask:0xf bank_mask:0xf
	v_add_f32_e32 v132, v128, v129
	s_waitcnt vmcnt(37)
; #define LAS __attribute__((address_space(3)))
; __device__ __forceinline__ float red8(float v) { v += dpp_f<0xB1>(v); v += dpp_f<0x4E>(v); v += dpp_f<0x141>(v); return v; }
; __device__ __forceinline__ void kv8_qk(const u32x4 (&buf)[8], const f32x2v (&q2)[8], LAS float* srow, int b, int lane) {
; #pragma unroll
;     for (int u = 0; u < 8; ++u) {
;         const u32x4 k = buf[u];
;         f32x2v s0 = q2[0] * __builtin_amdgcn_cvt_pk_f32_fp8(k.x, false), s1 = q2[1] * __builtin_amdgcn_cvt_pk_f32_fp8(k.x, true);
;         s0 = __builtin_elementwise_fma(q2[2], __builtin_amdgcn_cvt_pk_f32_fp8(k.y, false), s0); s1 = __builtin_elementwise_fma(q2[3], __builtin_amdgcn_cvt_pk_f32_fp8(k.y, true), s1);
;         s0 = __builtin_elementwise_fma(q2[4], __builtin_amdgcn_cvt_pk_f32_fp8(k.z, false), s0); s1 = __builtin_elementwise_fma(q2[5], __builtin_amdgcn_cvt_pk_f32_fp8(k.z, true), s1);
;         s0 = __builtin_elementwise_fma(q2[6], __builtin_amdgcn_cvt_pk_f32_fp8(k.w, false), s0); s1 = __builtin_elementwise_fma(q2[7], __builtin_amdgcn_cvt_pk_f32_fp8(k.w, true), s1);
;         const f32x2v t = s0 + s1;
;         const float s = red8(t.x + t.y);
;         if ((lane & 7) == 0) srow[b * 8 + u] = s;
;     }
; }
	v_cvt_pk_f32_fp8_e32 v[214:215], v60
	v_cvt_pk_f32_fp8_sdwa v[216:217], v60 src0_sel:WORD_1
	v_pk_mul_f32 v[128:129], v[214:215], v[182:183]
	v_cvt_pk_f32_fp8_e32 v[218:219], v61
	v_add_f32_dpp v132, v132, v132 quad_perm:[1,0,3,2] row_mask:0xf bank_mask:0xf
	v_pk_fma_f32 v[128:129], v[184:185], v[216:217], v[128:129]
	v_cvt_pk_f32_fp8_sdwa v[220:221], v61 src0_sel:WORD_1
	v_pk_fma_f32 v[128:129], v[186:187], v[218:219], v[128:129]
	v_cvt_pk_f32_fp8_e32 v[222:223], v62
	v_pk_fma_f32 v[128:129], v[188:189], v[220:221], v[128:129]
	v_cvt_pk_f32_fp8_sdwa v[224:225], v62 src0_sel:WORD_1
	v_add_f32_dpp v132, v132, v132 quad_perm:[2,3,0,1] row_mask:0xf bank_mask:0xf
	v_pk_fma_f32 v[128:129], v[190:191], v[222:223], v[128:129]
	v_cvt_pk_f32_fp8_e32 v[226:227], v63
	v_pk_fma_f32 v[128:129], v[192:193], v[224:225], v[128:129]
	v_cvt_pk_f32_fp8_sdwa v[228:229], v63 src0_sel:WORD_1
	v_pk_fma_f32 v[128:129], v[194:195], v[226:227], v[128:129]
	v_pk_fma_f32 v[128:129], v[196:197], v[228:229], v[128:129]
	buffer_load_dwordx4 v[60:63], v165, s[16:19], s27 offen sc0
	v_add_f32_dpp v164, v132, v132 row_half_mirror row_mask:0xf bank_mask:0xf
	v_add_f32_e32 v133, v128, v129
	s_waitcnt vmcnt(37)
	v_cvt_pk_f32_fp8_e32 v[214:215], v64
	v_cvt_pk_f32_fp8_sdwa v[216:217], v64 src0_sel:WORD_1
	v_pk_mul_f32 v[128:129], v[214:215], v[182:183]
	v_cvt_pk_f32_fp8_e32 v[218:219], v65
	v_add_f32_dpp v133, v133, v133 quad_perm:[1,0,3,2] row_mask:0xf bank_mask:0xf
	v_pk_fma_f32 v[128:129], v[184:185], v[216:217], v[128:129]
	v_cvt_pk_f32_fp8_sdwa v[220:221], v65 src0_sel:WORD_1
	v_pk_fma_f32 v[128:129], v[186:187], v[218:219], v[128:129]
	v_cvt_pk_f32_fp8_e32 v[222:223], v66
	v_pk_fma_f32 v[128:129], v[188:189], v[220:221], v[128:129]
	v_cvt_pk_f32_fp8_sdwa v[224:225], v66 src0_sel:WORD_1
	v_add_f32_dpp v133, v133, v133 quad_perm:[2,3,0,1] row_mask:0xf bank_mask:0xf
	v_pk_fma_f32 v[128:129], v[190:191], v[222:223], v[128:129]
	v_cvt_pk_f32_fp8_e32 v[226:227], v67
	v_pk_fma_f32 v[128:129], v[192:193], v[224:225], v[128:129]
	v_cvt_pk_f32_fp8_sdwa v[228:229], v67 src0_sel:WORD_1
	v_pk_fma_f32 v[128:129], v[194:195], v[226:227], v[128:129]
	v_pk_fma_f32 v[128:129], v[196:197], v[228:229], v[128:129]
	buffer_load_dwordx4 v[64:67], v166, s[16:19], s27 offen sc0
	v_add_f32_dpp v165, v133, v133 row_half_mirror row_mask:0xf bank_mask:0xf
	v_add_f32_e32 v132, v128, v129
	s_waitcnt vmcnt(37)
	v_cvt_pk_f32_fp8_e32 v[214:215], v68
	v_cvt_pk_f32_fp8_sdwa v[216:217], v68 src0_sel:WORD_1
	v_pk_mul_f32 v[128:129], v[214:215], v[182:183]
	v_cvt_pk_f32_fp8_e32 v[218:219], v69
	v_add_f32_dpp v132, v132, v132 quad_perm:[1,0,3,2] row_mask:0xf bank_mask:0xf
	v_pk_fma_f32 v[128:129], v[184:185], v[216:217], v[128:129]
	v_cvt_pk_f32_fp8_sdwa v[220:221], v69 src0_sel:WORD_1
	v_pk_fma_f32 v[128:129], v[186:187], v[218:219], v[128:129]
	v_cvt_pk_f32_fp8_e32 v[222:223], v70
	v_pk_fma_f32 v[128:129], v[188:189], v[220:221], v[128:129]
	v_cvt_pk_f32_fp8_sdwa v[224:225], v70 src0_sel:WORD_1
	v_add_f32_dpp v132, v132, v132 quad_perm:[2,3,0,1] row_mask:0xf bank_mask:0xf
	v_pk_fma_f32 v[128:129], v[190:191], v[222:223], v[128:129]
	v_cvt_pk_f32_fp8_e32 v[226:227], v71
	v_pk_fma_f32 v[128:129], v[192:193], v[224:225], v[128:129]
	v_cvt_pk_f32_fp8_sdwa v[228:229], v71 src0_sel:WORD_1
	v_pk_fma_f32 v[128:129], v[194:195], v[226:227], v[128:129]
	v_pk_fma_f32 v[128:129], v[196:197], v[228:229], v[128:129]
	buffer_load_dwordx4 v[68:71], v167, s[16:19], s27 offen sc0
	v_add_f32_dpp v166, v132, v132 row_half_mirror row_mask:0xf bank_mask:0xf
	v_add_f32_e32 v133, v128, v129
	s_waitcnt vmcnt(37)
	v_cvt_pk_f32_fp8_e32 v[214:215], v72
	v_cvt_pk_f32_fp8_sdwa v[216:217], v72 src0_sel:WORD_1
	v_pk_mul_f32 v[128:129], v[214:215], v[182:183]
	v_cvt_pk_f32_fp8_e32 v[218:219], v73
	v_add_f32_dpp v133, v133, v133 quad_perm:[1,0,3,2] row_mask:0xf bank_mask:0xf
	v_pk_fma_f32 v[128:129], v[184:185], v[216:217], v[128:129]
	v_cvt_pk_f32_fp8_sdwa v[220:221], v73 src0_sel:WORD_1
	v_pk_fma_f32 v[128:129], v[186:187], v[218:219], v[128:129]
	v_cvt_pk_f32_fp8_e32 v[222:223], v74
	v_pk_fma_f32 v[128:129], v[188:189], v[220:221], v[128:129]
	v_cvt_pk_f32_fp8_sdwa v[224:225], v74 src0_sel:WORD_1
	v_add_f32_dpp v133, v133, v133 quad_perm:[2,3,0,1] row_mask:0xf bank_mask:0xf
	v_pk_fma_f32 v[128:129], v[190:191], v[222:223], v[128:129]
	v_cvt_pk_f32_fp8_e32 v[226:227], v75
	v_pk_fma_f32 v[128:129], v[192:193], v[224:225], v[128:129]
	v_cvt_pk_f32_fp8_sdwa v[228:229], v75 src0_sel:WORD_1
	v_pk_fma_f32 v[128:129], v[194:195], v[226:227], v[128:129]
	v_pk_fma_f32 v[128:129], v[196:197], v[228:229], v[128:129]
	buffer_load_dwordx4 v[72:75], v168, s[16:19], s27 offen sc0
	v_add_f32_dpp v167, v133, v133 row_half_mirror row_mask:0xf bank_mask:0xf
	v_add_f32_e32 v132, v128, v129
	s_waitcnt vmcnt(37)
	v_cvt_pk_f32_fp8_e32 v[214:215], v76
	v_cvt_pk_f32_fp8_sdwa v[216:217], v76 src0_sel:WORD_1
	v_pk_mul_f32 v[128:129], v[214:215], v[182:183]
	v_cvt_pk_f32_fp8_e32 v[218:219], v77
	v_add_f32_dpp v132, v132, v132 quad_perm:[1,0,3,2] row_mask:0xf bank_mask:0xf
	v_pk_fma_f32 v[128:129], v[184:185], v[216:217], v[128:129]
	v_cvt_pk_f32_fp8_sdwa v[220:221], v77 src0_sel:WORD_1
	v_pk_fma_f32 v[128:129], v[186:187], v[218:219], v[128:129]
	v_cvt_pk_f32_fp8_e32 v[222:223], v78
	v_pk_fma_f32 v[128:129], v[188:189], v[220:221], v[128:129]
	v_cvt_pk_f32_fp8_sdwa v[224:225], v78 src0_sel:WORD_1
	v_add_f32_dpp v132, v132, v132 quad_perm:[2,3,0,1] row_mask:0xf bank_mask:0xf
	v_pk_fma_f32 v[128:129], v[190:191], v[222:223], v[128:129]
	v_cvt_pk_f32_fp8_e32 v[226:227], v79
	v_pk_fma_f32 v[128:129], v[192:193], v[224:225], v[128:129]
	v_cvt_pk_f32_fp8_sdwa v[228:229], v79 src0_sel:WORD_1
	v_pk_fma_f32 v[128:129], v[194:195], v[226:227], v[128:129]
	v_pk_fma_f32 v[128:129], v[196:197], v[228:229], v[128:129]
	buffer_load_dwordx4 v[76:79], v169, s[16:19], s27 offen sc0
	v_add_f32_dpp v168, v132, v132 row_half_mirror row_mask:0xf bank_mask:0xf
	v_add_f32_e32 v133, v128, v129
	s_waitcnt vmcnt(37)
; #define LAS __attribute__((address_space(3)))
; __device__ __forceinline__ float red8(float v) { v += dpp_f<0xB1>(v); v += dpp_f<0x4E>(v); v += dpp_f<0x141>(v); return v; }
; __device__ __forceinline__ void kv8_qk(const u32x4 (&buf)[8], const f32x2v (&q2)[8], LAS float* srow, int b, int lane) {
; #pragma unroll
;     for (int u = 0; u < 8; ++u) {
;         const u32x4 k = buf[u];
;         f32x2v s0 = q2[0] * __builtin_amdgcn_cvt_pk_f32_fp8(k.x, false), s1 = q2[1] * __builtin_amdgcn_cvt_pk_f32_fp8(k.x, true);
;         s0 = __builtin_elementwise_fma(q2[2], __builtin_amdgcn_cvt_pk_f32_fp8(k.y, false), s0); s1 = __builtin_elementwise_fma(q2[3], __builtin_amdgcn_cvt_pk_f32_fp8(k.y, true), s1);
;         s0 = __builtin_elementwise_fma(q2[4], __builtin_amdgcn_cvt_pk_f32_fp8(k.z, false), s0); s1 = __builtin_elementwise_fma(q2[5], __builtin_amdgcn_cvt_pk_f32_fp8(k.z, true), s1);
;         s0 = __builtin_elementwise_fma(q2[6], __builtin_amdgcn_cvt_pk_f32_fp8(k.w, false), s0); s1 = __builtin_elementwise_fma(q2[7], __builtin_amdgcn_cvt_pk_f32_fp8(k.w, true), s1);
;         const f32x2v t = s0 + s1;
;         const float s = red8(t.x + t.y);
;         if ((lane & 7) == 0) srow[b * 8 + u] = s;
;     }
; }
	v_cvt_pk_f32_fp8_e32 v[214:215], v80
	v_cvt_pk_f32_fp8_sdwa v[216:217], v80 src0_sel:WORD_1
	v_pk_mul_f32 v[128:129], v[214:215], v[182:183]
	v_cvt_pk_f32_fp8_e32 v[218:219], v81
	v_add_f32_dpp v133, v133, v133 quad_perm:[1,0,3,2] row_mask:0xf bank_mask:0xf
	v_pk_fma_f32 v[128:129], v[184:185], v[216:217], v[128:129]
	v_cvt_pk_f32_fp8_sdwa v[220:221], v81 src0_sel:WORD_1
	v_pk_fma_f32 v[128:129], v[186:187], v[218:219], v[128:129]
	v_cvt_pk_f32_fp8_e32 v[222:223], v82
	v_pk_fma_f32 v[128:129], v[188:189], v[220:221], v[128:129]
	v_cvt_pk_f32_fp8_sdwa v[224:225], v82 src0_sel:WORD_1
	v_add_f32_dpp v133, v133, v133 quad_perm:[2,3,0,1] row_mask:0xf bank_mask:0xf
	v_pk_fma_f32 v[128:129], v[190:191], v[222:223], v[128:129]
	v_cvt_pk_f32_fp8_e32 v[226:227], v83
	v_pk_fma_f32 v[128:129], v[192:193], v[224:225], v[128:129]
	v_cvt_pk_f32_fp8_sdwa v[228:229], v83 src0_sel:WORD_1
	v_pk_fma_f32 v[128:129], v[194:195], v[226:227], v[128:129]
	v_pk_fma_f32 v[128:129], v[196:197], v[228:229], v[128:129]
	buffer_load_dwordx4 v[80:83], v170, s[16:19], s27 offen sc0
	v_add_f32_dpp v169, v133, v133 row_half_mirror row_mask:0xf bank_mask:0xf
	v_add_f32_e32 v132, v128, v129
	s_waitcnt vmcnt(37)
	v_cvt_pk_f32_fp8_e32 v[214:215], v84
	v_cvt_pk_f32_fp8_sdwa v[216:217], v84 src0_sel:WORD_1
	v_pk_mul_f32 v[128:129], v[214:215], v[182:183]
	v_cvt_pk_f32_fp8_e32 v[218:219], v85
	v_add_f32_dpp v132, v132, v132 quad_perm:[1,0,3,2] row_mask:0xf bank_mask:0xf
	v_pk_fma_f32 v[128:129], v[184:185], v[216:217], v[128:129]
	v_cvt_pk_f32_fp8_sdwa v[220:221], v85 src0_sel:WORD_1
	v_pk_fma_f32 v[128:129], v[186:187], v[218:219], v[128:129]
	v_cvt_pk_f32_fp8_e32 v[222:223], v86
	v_pk_fma_f32 v[128:129], v[188:189], v[220:221], v[128:129]
	v_cvt_pk_f32_fp8_sdwa v[224:225], v86 src0_sel:WORD_1
	v_add_f32_dpp v132, v132, v132 quad_perm:[2,3,0,1] row_mask:0xf bank_mask:0xf
	v_pk_fma_f32 v[128:129], v[190:191], v[222:223], v[128:129]
	v_cvt_pk_f32_fp8_e32 v[226:227], v87
	v_pk_fma_f32 v[128:129], v[192:193], v[224:225], v[128:129]
	v_cvt_pk_f32_fp8_sdwa v[228:229], v87 src0_sel:WORD_1
	v_pk_fma_f32 v[128:129], v[194:195], v[226:227], v[128:129]
	v_pk_fma_f32 v[128:129], v[196:197], v[228:229], v[128:129]
	buffer_load_dwordx4 v[84:87], v171, s[16:19], s27 offen sc0
	v_add_f32_dpp v170, v132, v132 row_half_mirror row_mask:0xf bank_mask:0xf
	v_add_f32_e32 v133, v128, v129
	s_waitcnt vmcnt(37)
	v_cvt_pk_f32_fp8_e32 v[214:215], v88
	v_cvt_pk_f32_fp8_sdwa v[216:217], v88 src0_sel:WORD_1
	v_pk_mul_f32 v[128:129], v[214:215], v[182:183]
	v_cvt_pk_f32_fp8_e32 v[218:219], v89
	v_add_f32_dpp v133, v133, v133 quad_perm:[1,0,3,2] row_mask:0xf bank_mask:0xf
	v_pk_fma_f32 v[128:129], v[184:185], v[216:217], v[128:129]
	v_cvt_pk_f32_fp8_sdwa v[220:221], v89 src0_sel:WORD_1
	v_pk_fma_f32 v[128:129], v[186:187], v[218:219], v[128:129]
	v_cvt_pk_f32_fp8_e32 v[222:223], v90
	v_pk_fma_f32 v[128:129], v[188:189], v[220:221], v[128:129]
	v_cvt_pk_f32_fp8_sdwa v[224:225], v90 src0_sel:WORD_1
	v_add_f32_dpp v133, v133, v133 quad_perm:[2,3,0,1] row_mask:0xf bank_mask:0xf
	v_pk_fma_f32 v[128:129], v[190:191], v[222:223], v[128:129]
	v_cvt_pk_f32_fp8_e32 v[226:227], v91
	v_pk_fma_f32 v[128:129], v[192:193], v[224:225], v[128:129]
	v_cvt_pk_f32_fp8_sdwa v[228:229], v91 src0_sel:WORD_1
	v_pk_fma_f32 v[128:129], v[194:195], v[226:227], v[128:129]
	v_pk_fma_f32 v[128:129], v[196:197], v[228:229], v[128:129]
	buffer_load_dwordx4 v[88:91], v172, s[16:19], s27 offen sc0
	v_add_f32_dpp v171, v133, v133 row_half_mirror row_mask:0xf bank_mask:0xf
	v_add_f32_e32 v132, v128, v129
	s_waitcnt vmcnt(37)
	v_cvt_pk_f32_fp8_e32 v[214:215], v92
	v_cvt_pk_f32_fp8_sdwa v[216:217], v92 src0_sel:WORD_1
	v_pk_mul_f32 v[128:129], v[214:215], v[182:183]
	v_cvt_pk_f32_fp8_e32 v[218:219], v93
	v_add_f32_dpp v132, v132, v132 quad_perm:[1,0,3,2] row_mask:0xf bank_mask:0xf
	v_pk_fma_f32 v[128:129], v[184:185], v[216:217], v[128:129]
	v_cvt_pk_f32_fp8_sdwa v[220:221], v93 src0_sel:WORD_1
	v_pk_fma_f32 v[128:129], v[186:187], v[218:219], v[128:129]
	v_cvt_pk_f32_fp8_e32 v[222:223], v94
	v_pk_fma_f32 v[128:129], v[188:189], v[220:221], v[128:129]
	v_cvt_pk_f32_fp8_sdwa v[224:225], v94 src0_sel:WORD_1
	v_add_f32_dpp v132, v132, v132 quad_perm:[2,3,0,1] row_mask:0xf bank_mask:0xf
	v_pk_fma_f32 v[128:129], v[190:191], v[222:223], v[128:129]
	v_cvt_pk_f32_fp8_e32 v[226:227], v95
	v_pk_fma_f32 v[128:129], v[192:193], v[224:225], v[128:129]
	v_cvt_pk_f32_fp8_sdwa v[228:229], v95 src0_sel:WORD_1
	v_pk_fma_f32 v[128:129], v[194:195], v[226:227], v[128:129]
	v_pk_fma_f32 v[128:129], v[196:197], v[228:229], v[128:129]
	buffer_load_dwordx4 v[92:95], v173, s[16:19], s27 offen sc0
	v_add_f32_dpp v172, v132, v132 row_half_mirror row_mask:0xf bank_mask:0xf
	v_add_f32_e32 v133, v128, v129
	s_waitcnt vmcnt(37)
	v_cvt_pk_f32_fp8_e32 v[214:215], v96
	v_cvt_pk_f32_fp8_sdwa v[216:217], v96 src0_sel:WORD_1
	v_pk_mul_f32 v[128:129], v[214:215], v[182:183]
	v_cvt_pk_f32_fp8_e32 v[218:219], v97
	v_add_f32_dpp v133, v133, v133 quad_perm:[1,0,3,2] row_mask:0xf bank_mask:0xf
	v_pk_fma_f32 v[128:129], v[184:185], v[216:217], v[128:129]
	v_cvt_pk_f32_fp8_sdwa v[220:221], v97 src0_sel:WORD_1
	v_pk_fma_f32 v[128:129], v[186:187], v[218:219], v[128:129]
	v_cvt_pk_f32_fp8_e32 v[222:223], v98
	v_pk_fma_f32 v[128:129], v[188:189], v[220:221], v[128:129]
	v_cvt_pk_f32_fp8_sdwa v[224:225], v98 src0_sel:WORD_1
	v_add_f32_dpp v133, v133, v133 quad_perm:[2,3,0,1] row_mask:0xf bank_mask:0xf
	v_pk_fma_f32 v[128:129], v[190:191], v[222:223], v[128:129]
	v_cvt_pk_f32_fp8_e32 v[226:227], v99
	v_pk_fma_f32 v[128:129], v[192:193], v[224:225], v[128:129]
	v_cvt_pk_f32_fp8_sdwa v[228:229], v99 src0_sel:WORD_1
	v_pk_fma_f32 v[128:129], v[194:195], v[226:227], v[128:129]
	v_pk_fma_f32 v[128:129], v[196:197], v[228:229], v[128:129]
	buffer_load_dwordx4 v[96:99], v174, s[16:19], s27 offen sc0
	v_add_f32_dpp v173, v133, v133 row_half_mirror row_mask:0xf bank_mask:0xf
	v_add_f32_e32 v132, v128, v129
	s_waitcnt vmcnt(37)
; #define LAS __attribute__((address_space(3)))
; __device__ __forceinline__ float red8(float v) { v += dpp_f<0xB1>(v); v += dpp_f<0x4E>(v); v += dpp_f<0x141>(v); return v; }
; __device__ __forceinline__ void kv8_qk(const u32x4 (&buf)[8], const f32x2v (&q2)[8], LAS float* srow, int b, int lane) {
; #pragma unroll
;     for (int u = 0; u < 8; ++u) {
;         const u32x4 k = buf[u];
;         f32x2v s0 = q2[0] * __builtin_amdgcn_cvt_pk_f32_fp8(k.x, false), s1 = q2[1] * __builtin_amdgcn_cvt_pk_f32_fp8(k.x, true);
;         s0 = __builtin_elementwise_fma(q2[2], __builtin_amdgcn_cvt_pk_f32_fp8(k.y, false), s0); s1 = __builtin_elementwise_fma(q2[3], __builtin_amdgcn_cvt_pk_f32_fp8(k.y, true), s1);
;         s0 = __builtin_elementwise_fma(q2[4], __builtin_amdgcn_cvt_pk_f32_fp8(k.z, false), s0); s1 = __builtin_elementwise_fma(q2[5], __builtin_amdgcn_cvt_pk_f32_fp8(k.z, true), s1);
;         s0 = __builtin_elementwise_fma(q2[6], __builtin_amdgcn_cvt_pk_f32_fp8(k.w, false), s0); s1 = __builtin_elementwise_fma(q2[7], __builtin_amdgcn_cvt_pk_f32_fp8(k.w, true), s1);
;         const f32x2v t = s0 + s1;
;         const float s = red8(t.x + t.y);
;         if ((lane & 7) == 0) srow[b * 8 + u] = s;
;     }
; }
	v_cvt_pk_f32_fp8_e32 v[214:215], v100
	v_cvt_pk_f32_fp8_sdwa v[216:217], v100 src0_sel:WORD_1
	v_pk_mul_f32 v[128:129], v[214:215], v[182:183]
	v_cvt_pk_f32_fp8_e32 v[218:219], v101
	v_add_f32_dpp v132, v132, v132 quad_perm:[1,0,3,2] row_mask:0xf bank_mask:0xf
	v_pk_fma_f32 v[128:129], v[184:185], v[216:217], v[128:129]
	v_cvt_pk_f32_fp8_sdwa v[220:221], v101 src0_sel:WORD_1
	v_pk_fma_f32 v[128:129], v[186:187], v[218:219], v[128:129]
	v_cvt_pk_f32_fp8_e32 v[222:223], v102
	v_pk_fma_f32 v[128:129], v[188:189], v[220:221], v[128:129]
	v_cvt_pk_f32_fp8_sdwa v[224:225], v102 src0_sel:WORD_1
	v_add_f32_dpp v132, v132, v132 quad_perm:[2,3,0,1] row_mask:0xf bank_mask:0xf
	v_pk_fma_f32 v[128:129], v[190:191], v[222:223], v[128:129]
	v_cvt_pk_f32_fp8_e32 v[226:227], v103
	v_pk_fma_f32 v[128:129], v[192:193], v[224:225], v[128:129]
	v_cvt_pk_f32_fp8_sdwa v[228:229], v103 src0_sel:WORD_1
	v_pk_fma_f32 v[128:129], v[194:195], v[226:227], v[128:129]
	v_pk_fma_f32 v[128:129], v[196:197], v[228:229], v[128:129]
	buffer_load_dwordx4 v[100:103], v175, s[16:19], s27 offen sc0
	v_add_f32_dpp v174, v132, v132 row_half_mirror row_mask:0xf bank_mask:0xf
	v_add_f32_e32 v133, v128, v129
	s_waitcnt vmcnt(37)
	v_cvt_pk_f32_fp8_e32 v[214:215], v104
	v_cvt_pk_f32_fp8_sdwa v[216:217], v104 src0_sel:WORD_1
	v_pk_mul_f32 v[128:129], v[214:215], v[182:183]
	v_cvt_pk_f32_fp8_e32 v[218:219], v105
	v_add_f32_dpp v133, v133, v133 quad_perm:[1,0,3,2] row_mask:0xf bank_mask:0xf
	v_pk_fma_f32 v[128:129], v[184:185], v[216:217], v[128:129]
	v_cvt_pk_f32_fp8_sdwa v[220:221], v105 src0_sel:WORD_1
	v_pk_fma_f32 v[128:129], v[186:187], v[218:219], v[128:129]
	v_cvt_pk_f32_fp8_e32 v[222:223], v106
	v_pk_fma_f32 v[128:129], v[188:189], v[220:221], v[128:129]
	v_cvt_pk_f32_fp8_sdwa v[224:225], v106 src0_sel:WORD_1
	v_add_f32_dpp v133, v133, v133 quad_perm:[2,3,0,1] row_mask:0xf bank_mask:0xf
	v_pk_fma_f32 v[128:129], v[190:191], v[222:223], v[128:129]
	v_cvt_pk_f32_fp8_e32 v[226:227], v107
	v_pk_fma_f32 v[128:129], v[192:193], v[224:225], v[128:129]
	v_cvt_pk_f32_fp8_sdwa v[228:229], v107 src0_sel:WORD_1
	v_pk_fma_f32 v[128:129], v[194:195], v[226:227], v[128:129]
	v_pk_fma_f32 v[128:129], v[196:197], v[228:229], v[128:129]
	buffer_load_dwordx4 v[104:107], v176, s[16:19], s27 offen sc0
	v_add_f32_dpp v175, v133, v133 row_half_mirror row_mask:0xf bank_mask:0xf
	v_add_f32_e32 v132, v128, v129
	s_waitcnt vmcnt(37)
	v_cvt_pk_f32_fp8_e32 v[214:215], v108
	v_cvt_pk_f32_fp8_sdwa v[216:217], v108 src0_sel:WORD_1
	v_pk_mul_f32 v[128:129], v[214:215], v[182:183]
	v_cvt_pk_f32_fp8_e32 v[218:219], v109
	v_add_f32_dpp v132, v132, v132 quad_perm:[1,0,3,2] row_mask:0xf bank_mask:0xf
	v_pk_fma_f32 v[128:129], v[184:185], v[216:217], v[128:129]
	v_cvt_pk_f32_fp8_sdwa v[220:221], v109 src0_sel:WORD_1
	v_pk_fma_f32 v[128:129], v[186:187], v[218:219], v[128:129]
	v_cvt_pk_f32_fp8_e32 v[222:223], v110
	v_pk_fma_f32 v[128:129], v[188:189], v[220:221], v[128:129]
	v_cvt_pk_f32_fp8_sdwa v[224:225], v110 src0_sel:WORD_1
	v_add_f32_dpp v132, v132, v132 quad_perm:[2,3,0,1] row_mask:0xf bank_mask:0xf
	v_pk_fma_f32 v[128:129], v[190:191], v[222:223], v[128:129]
	v_cvt_pk_f32_fp8_e32 v[226:227], v111
	v_pk_fma_f32 v[128:129], v[192:193], v[224:225], v[128:129]
	v_cvt_pk_f32_fp8_sdwa v[228:229], v111 src0_sel:WORD_1
	v_pk_fma_f32 v[128:129], v[194:195], v[226:227], v[128:129]
	v_pk_fma_f32 v[128:129], v[196:197], v[228:229], v[128:129]
	buffer_load_dwordx4 v[108:111], v177, s[16:19], s27 offen sc0
	v_add_f32_dpp v176, v132, v132 row_half_mirror row_mask:0xf bank_mask:0xf
	v_add_f32_e32 v133, v128, v129
	s_waitcnt vmcnt(37)
	v_cvt_pk_f32_fp8_e32 v[214:215], v112
	v_cvt_pk_f32_fp8_sdwa v[216:217], v112 src0_sel:WORD_1
	v_pk_mul_f32 v[128:129], v[214:215], v[182:183]
	v_cvt_pk_f32_fp8_e32 v[218:219], v113
	v_add_f32_dpp v133, v133, v133 quad_perm:[1,0,3,2] row_mask:0xf bank_mask:0xf
	v_pk_fma_f32 v[128:129], v[184:185], v[216:217], v[128:129]
	v_cvt_pk_f32_fp8_sdwa v[220:221], v113 src0_sel:WORD_1
	v_pk_fma_f32 v[128:129], v[186:187], v[218:219], v[128:129]
	v_cvt_pk_f32_fp8_e32 v[222:223], v114
	v_pk_fma_f32 v[128:129], v[188:189], v[220:221], v[128:129]
	v_cvt_pk_f32_fp8_sdwa v[224:225], v114 src0_sel:WORD_1
	v_add_f32_dpp v133, v133, v133 quad_perm:[2,3,0,1] row_mask:0xf bank_mask:0xf
	v_pk_fma_f32 v[128:129], v[190:191], v[222:223], v[128:129]
	v_cvt_pk_f32_fp8_e32 v[226:227], v115
	v_pk_fma_f32 v[128:129], v[192:193], v[224:225], v[128:129]
	v_cvt_pk_f32_fp8_sdwa v[228:229], v115 src0_sel:WORD_1
	v_pk_fma_f32 v[128:129], v[194:195], v[226:227], v[128:129]
	v_pk_fma_f32 v[128:129], v[196:197], v[228:229], v[128:129]
	buffer_load_dwordx4 v[112:115], v178, s[16:19], s27 offen sc0
	v_add_f32_dpp v177, v133, v133 row_half_mirror row_mask:0xf bank_mask:0xf
	v_add_f32_e32 v132, v128, v129
	s_waitcnt vmcnt(37)
	v_cvt_pk_f32_fp8_e32 v[214:215], v116
	v_cvt_pk_f32_fp8_sdwa v[216:217], v116 src0_sel:WORD_1
	v_pk_mul_f32 v[128:129], v[214:215], v[182:183]
	v_cvt_pk_f32_fp8_e32 v[218:219], v117
	v_add_f32_dpp v132, v132, v132 quad_perm:[1,0,3,2] row_mask:0xf bank_mask:0xf
	v_pk_fma_f32 v[128:129], v[184:185], v[216:217], v[128:129]
	v_cvt_pk_f32_fp8_sdwa v[220:221], v117 src0_sel:WORD_1
	v_pk_fma_f32 v[128:129], v[186:187], v[218:219], v[128:129]
	v_cvt_pk_f32_fp8_e32 v[222:223], v118
	v_pk_fma_f32 v[128:129], v[188:189], v[220:221], v[128:129]
	v_cvt_pk_f32_fp8_sdwa v[224:225], v118 src0_sel:WORD_1
	v_add_f32_dpp v132, v132, v132 quad_perm:[2,3,0,1] row_mask:0xf bank_mask:0xf
	v_pk_fma_f32 v[128:129], v[190:191], v[222:223], v[128:129]
	v_cvt_pk_f32_fp8_e32 v[226:227], v119
	v_pk_fma_f32 v[128:129], v[192:193], v[224:225], v[128:129]
	v_cvt_pk_f32_fp8_sdwa v[228:229], v119 src0_sel:WORD_1
	v_pk_fma_f32 v[128:129], v[194:195], v[226:227], v[128:129]
	v_pk_fma_f32 v[128:129], v[196:197], v[228:229], v[128:129]
	buffer_load_dwordx4 v[116:119], v179, s[16:19], s27 offen sc0
	v_add_f32_dpp v178, v132, v132 row_half_mirror row_mask:0xf bank_mask:0xf
	v_add_f32_e32 v133, v128, v129
	s_waitcnt vmcnt(37)
; #define LAS __attribute__((address_space(3)))
; __device__ __forceinline__ float red8(float v) { v += dpp_f<0xB1>(v); v += dpp_f<0x4E>(v); v += dpp_f<0x141>(v); return v; }
; __device__ __forceinline__ void kv8_qk(const u32x4 (&buf)[8], const f32x2v (&q2)[8], LAS float* srow, int b, int lane) {
; #pragma unroll
;     for (int u = 0; u < 8; ++u) {
;         const u32x4 k = buf[u];
;         f32x2v s0 = q2[0] * __builtin_amdgcn_cvt_pk_f32_fp8(k.x, false), s1 = q2[1] * __builtin_amdgcn_cvt_pk_f32_fp8(k.x, true);
;         s0 = __builtin_elementwise_fma(q2[2], __builtin_amdgcn_cvt_pk_f32_fp8(k.y, false), s0); s1 = __builtin_elementwise_fma(q2[3], __builtin_amdgcn_cvt_pk_f32_fp8(k.y, true), s1);
;         s0 = __builtin_elementwise_fma(q2[4], __builtin_amdgcn_cvt_pk_f32_fp8(k.z, false), s0); s1 = __builtin_elementwise_fma(q2[5], __builtin_amdgcn_cvt_pk_f32_fp8(k.z, true), s1);
;         s0 = __builtin_elementwise_fma(q2[6], __builtin_amdgcn_cvt_pk_f32_fp8(k.w, false), s0); s1 = __builtin_elementwise_fma(q2[7], __builtin_amdgcn_cvt_pk_f32_fp8(k.w, true), s1);
;         const f32x2v t = s0 + s1;
;         const float s = red8(t.x + t.y);
;         if ((lane & 7) == 0) srow[b * 8 + u] = s;
;     }
; }
; __device__ __forceinline__ void attn_query8(const unsigned char* __restrict__ KV8, const bf16_t* __restrict__ Z, const int* __restrict__ SEL, bf16_t* __restrict__ YMIX, int t, LAS float* sbuf  ) {
;     ...
;     for (int h = 0; h < 8; ++h) {
;         float sv[4]; float mx = -__builtin_inff();
; #pragma unroll
;         for (int jj = 0; jj < 4; ++jj) { const int j = lane + 64 * jj; const float s = sbuf[h * 256 + j]; sv[jj] = (j < nsel) ? s : -__builtin_inff(); mx = fmaxf(mx, sv[jj]); }
	v_cvt_pk_f32_fp8_e32 v[214:215], v120
	v_cvt_pk_f32_fp8_sdwa v[216:217], v120 src0_sel:WORD_1
	v_pk_mul_f32 v[128:129], v[214:215], v[182:183]
	v_cvt_pk_f32_fp8_e32 v[218:219], v121
	v_add_f32_dpp v133, v133, v133 quad_perm:[1,0,3,2] row_mask:0xf bank_mask:0xf
	v_pk_fma_f32 v[128:129], v[184:185], v[216:217], v[128:129]
	v_cvt_pk_f32_fp8_sdwa v[220:221], v121 src0_sel:WORD_1
	v_pk_fma_f32 v[128:129], v[186:187], v[218:219], v[128:129]
	v_cvt_pk_f32_fp8_e32 v[222:223], v122
	v_pk_fma_f32 v[128:129], v[188:189], v[220:221], v[128:129]
	v_cvt_pk_f32_fp8_sdwa v[224:225], v122 src0_sel:WORD_1
	v_add_f32_dpp v133, v133, v133 quad_perm:[2,3,0,1] row_mask:0xf bank_mask:0xf
	v_pk_fma_f32 v[128:129], v[190:191], v[222:223], v[128:129]
	v_cvt_pk_f32_fp8_e32 v[226:227], v123
	v_pk_fma_f32 v[128:129], v[192:193], v[224:225], v[128:129]
	v_cvt_pk_f32_fp8_sdwa v[228:229], v123 src0_sel:WORD_1
	v_pk_fma_f32 v[128:129], v[194:195], v[226:227], v[128:129]
	v_pk_fma_f32 v[128:129], v[196:197], v[228:229], v[128:129]
	buffer_load_dwordx4 v[120:123], v180, s[16:19], s27 offen sc0
	v_add_f32_dpp v179, v133, v133 row_half_mirror row_mask:0xf bank_mask:0xf
	v_add_f32_e32 v132, v128, v129
	s_waitcnt vmcnt(37)
	v_cvt_pk_f32_fp8_e32 v[214:215], v124
	v_cvt_pk_f32_fp8_sdwa v[216:217], v124 src0_sel:WORD_1
	v_pk_mul_f32 v[128:129], v[214:215], v[182:183]
	v_cvt_pk_f32_fp8_e32 v[218:219], v125
	v_add_f32_dpp v132, v132, v132 quad_perm:[1,0,3,2] row_mask:0xf bank_mask:0xf
	v_pk_fma_f32 v[128:129], v[184:185], v[216:217], v[128:129]
	v_cvt_pk_f32_fp8_sdwa v[220:221], v125 src0_sel:WORD_1
	v_pk_fma_f32 v[128:129], v[186:187], v[218:219], v[128:129]
	v_cvt_pk_f32_fp8_e32 v[222:223], v126
	v_pk_fma_f32 v[128:129], v[188:189], v[220:221], v[128:129]
	v_cvt_pk_f32_fp8_sdwa v[224:225], v126 src0_sel:WORD_1
	v_add_f32_dpp v132, v132, v132 quad_perm:[2,3,0,1] row_mask:0xf bank_mask:0xf
	v_pk_fma_f32 v[128:129], v[190:191], v[222:223], v[128:129]
	v_cvt_pk_f32_fp8_e32 v[226:227], v127
	v_pk_fma_f32 v[128:129], v[192:193], v[224:225], v[128:129]
	v_cvt_pk_f32_fp8_sdwa v[228:229], v127 src0_sel:WORD_1
	v_pk_fma_f32 v[128:129], v[194:195], v[226:227], v[128:129]
	v_pk_fma_f32 v[128:129], v[196:197], v[228:229], v[128:129]
	buffer_load_dwordx4 v[124:127], v181, s[16:19], s27 offen sc0
	v_add_f32_dpp v180, v132, v132 row_half_mirror row_mask:0xf bank_mask:0xf
	v_add_f32_e32 v133, v128, v129
	s_nop 1
	v_add_f32_dpp v133, v133, v133 quad_perm:[1,0,3,2] row_mask:0xf bank_mask:0xf
	s_nop 1
	v_add_f32_dpp v133, v133, v133 quad_perm:[2,3,0,1] row_mask:0xf bank_mask:0xf
	s_nop 1
	v_add_f32_dpp v181, v133, v133 row_half_mirror row_mask:0xf bank_mask:0xf
	s_cmpk_eq_i32 s4, 0x100
	s_cbranch_scc1 .Latt_nomask
	v_cmp_lt_i32_e32 vcc, 0, v143
	s_nop 1
	v_cndmask_b32_e32 v150, v142, v150, vcc
	v_cmp_lt_i32_e32 vcc, 8, v143
	s_nop 1
	v_cndmask_b32_e32 v151, v142, v151, vcc
	v_cmp_lt_i32_e32 vcc, 16, v143
	s_nop 1
	v_cndmask_b32_e32 v152, v142, v152, vcc
	v_cmp_lt_i32_e32 vcc, 24, v143
	s_nop 1
	v_cndmask_b32_e32 v153, v142, v153, vcc
	v_cmp_lt_i32_e32 vcc, 32, v143
	s_nop 1
	v_cndmask_b32_e32 v154, v142, v154, vcc
	v_cmp_lt_i32_e32 vcc, 40, v143
	s_nop 1
	v_cndmask_b32_e32 v155, v142, v155, vcc
	v_cmp_lt_i32_e32 vcc, 48, v143
	s_nop 1
	v_cndmask_b32_e32 v156, v142, v156, vcc
	v_cmp_lt_i32_e32 vcc, 56, v143
	s_nop 1
	v_cndmask_b32_e32 v157, v142, v157, vcc
	v_cmp_lt_i32_e32 vcc, 64, v143
	s_nop 1
	v_cndmask_b32_e32 v158, v142, v158, vcc
	v_cmp_lt_i32_e32 vcc, 0x48, v143
	s_nop 1
	v_cndmask_b32_e32 v159, v142, v159, vcc
	v_cmp_lt_i32_e32 vcc, 0x50, v143
	s_nop 1
	v_cndmask_b32_e32 v160, v142, v160, vcc
	v_cmp_lt_i32_e32 vcc, 0x58, v143
	s_nop 1
	v_cndmask_b32_e32 v161, v142, v161, vcc
	v_cmp_lt_i32_e32 vcc, 0x60, v143
	s_nop 1
	v_cndmask_b32_e32 v162, v142, v162, vcc
	v_cmp_lt_i32_e32 vcc, 0x68, v143
	s_nop 1
	v_cndmask_b32_e32 v163, v142, v163, vcc
	v_cmp_lt_i32_e32 vcc, 0x70, v143
	s_nop 1
	v_cndmask_b32_e32 v164, v142, v164, vcc
	v_cmp_lt_i32_e32 vcc, 0x78, v143
	s_nop 1
	v_cndmask_b32_e32 v165, v142, v165, vcc
	v_cmp_lt_i32_e32 vcc, 0x80, v143
	s_nop 1
	v_cndmask_b32_e32 v166, v142, v166, vcc
	v_cmp_lt_i32_e32 vcc, 0x88, v143
	s_nop 1
	v_cndmask_b32_e32 v167, v142, v167, vcc
	v_cmp_lt_i32_e32 vcc, 0x90, v143
	s_nop 1
	v_cndmask_b32_e32 v168, v142, v168, vcc
	v_cmp_lt_i32_e32 vcc, 0x98, v143
	s_nop 1
	v_cndmask_b32_e32 v169, v142, v169, vcc
	v_cmp_lt_i32_e32 vcc, 0xa0, v143
	s_nop 1
	v_cndmask_b32_e32 v170, v142, v170, vcc
	v_cmp_lt_i32_e32 vcc, 0xa8, v143
	s_nop 1
	v_cndmask_b32_e32 v171, v142, v171, vcc
	v_cmp_lt_i32_e32 vcc, 0xb0, v143
	s_nop 1
	v_cndmask_b32_e32 v172, v142, v172, vcc
	v_cmp_lt_i32_e32 vcc, 0xb8, v143
	s_nop 1
	v_cndmask_b32_e32 v173, v142, v173, vcc
	v_cmp_lt_i32_e32 vcc, 0xc0, v143
	s_nop 1
	v_cndmask_b32_e32 v174, v142, v174, vcc
	v_cmp_lt_i32_e32 vcc, 0xc8, v143
	s_nop 1
	v_cndmask_b32_e32 v175, v142, v175, vcc
	v_cmp_lt_i32_e32 vcc, 0xd0, v143
	s_nop 1
	v_cndmask_b32_e32 v176, v142, v176, vcc
	v_cmp_lt_i32_e32 vcc, 0xd8, v143
	s_nop 1
	v_cndmask_b32_e32 v177, v142, v177, vcc
	v_cmp_lt_i32_e32 vcc, 0xe0, v143
	s_nop 1
	v_cndmask_b32_e32 v178, v142, v178, vcc
	v_cmp_lt_i32_e32 vcc, 0xe8, v143
	s_nop 1
	v_cndmask_b32_e32 v179, v142, v179, vcc
	v_cmp_lt_i32_e32 vcc, 0xf0, v143
	s_nop 1
	v_cndmask_b32_e32 v180, v142, v180, vcc
	v_cmp_lt_i32_e32 vcc, 0xf8, v143
	s_nop 1
	v_cndmask_b32_e32 v181, v142, v181, vcc
; #define LAS __attribute__((address_space(3)))
; #define LDS_WAIT() asm volatile("s_waitcnt lgkmcnt(0)" ::: "memory")
; __device__ __forceinline__ void kv8_pv(const u32x4 (&buf)[8], f32x2v (&o2)[8], const LAS float* srow, int b) {
;     const LAS f32x4* p4 = (const LAS f32x4*)(srow + b * 8);
;     const f32x4 p0 = p4[0], p1 = p4[1];
;     const float p[8] = {p0.x, p0.y, p0.z, p0.w, p1.x, p1.y, p1.z, p1.w};
; #pragma unroll
;     for (int u = 0; u < 8; ++u) {
;         const u32x4 v = buf[u]; const f32x2v pp = {p[u], p[u]};
;         o2[0] = __builtin_elementwise_fma(pp, __builtin_amdgcn_cvt_pk_f32_fp8(v.x, false), o2[0]); o2[1] = __builtin_elementwise_fma(pp, __builtin_amdgcn_cvt_pk_f32_fp8(v.x, true), o2[1]);
;         o2[2] = __builtin_elementwise_fma(pp, __builtin_amdgcn_cvt_pk_f32_fp8(v.y, false), o2[2]); o2[3] = __builtin_elementwise_fma(pp, __builtin_amdgcn_cvt_pk_f32_fp8(v.y, true), o2[3]);
;         o2[4] = __builtin_elementwise_fma(pp, __builtin_amdgcn_cvt_pk_f32_fp8(v.z, false), o2[4]); o2[5] = __builtin_elementwise_fma(pp, __builtin_amdgcn_cvt_pk_f32_fp8(v.z, true), o2[5]);
;         o2[6] = __builtin_elementwise_fma(pp, __builtin_amdgcn_cvt_pk_f32_fp8(v.w, false), o2[6]); o2[7] = __builtin_elementwise_fma(pp, __builtin_amdgcn_cvt_pk_f32_fp8(v.w, true), o2[7]);
;     }
; __device__ __forceinline__ void attn_query8(const unsigned char* __restrict__ KV8, const bf16_t* __restrict__ Z, const int* __restrict__ SEL, bf16_t* __restrict__ YMIX, int t, LAS float* sbuf  ) {
;     ...
;     for (int h = 0; h < 8; ++h) {
;         float sv[4]; float mx = -__builtin_inff();
; #pragma unroll
;         for (int jj = 0; jj < 4; ++jj) { const int j = lane + 64 * jj; const float s = sbuf[h * 256 + j]; sv[jj] = (j < nsel) ? s : -__builtin_inff(); mx = fmaxf(mx, sv[jj]); }
;         mx = wave_max(mx); float sm = 0.f;
; #pragma unroll
;         for (int jj = 0; jj < 4; ++jj) { const int j = lane + 64 * jj; sv[jj] = (j < nsel) ? __expf(sv[jj] - mx) : 0.f; sm += sv[jj]; }
;         sm = wave_sum(sm); const float inv = 1.f / sm;
; #pragma unroll
;         for (int jj = 0; jj < 4; ++jj) sbuf[h * 256 + lane + 64 * jj] = sv[jj] * inv;
;     }
;     LDS_WAIT();
.Latt_nomask:
	v_max3_f32 v134, v150, v151, v152
	v_max3_f32 v134, v134, v153, v154
	v_max3_f32 v134, v134, v155, v156
	v_max3_f32 v134, v134, v157, v158
	v_max3_f32 v134, v134, v159, v160
	v_max3_f32 v134, v134, v161, v162
	v_max3_f32 v134, v134, v163, v164
	v_max3_f32 v134, v134, v165, v166
	v_max3_f32 v134, v134, v167, v168
	v_max3_f32 v134, v134, v169, v170
	v_max3_f32 v134, v134, v171, v172
	v_max3_f32 v134, v134, v173, v174
	v_max3_f32 v134, v134, v175, v176
	v_max3_f32 v134, v134, v177, v178
	v_max3_f32 v134, v134, v179, v180
	v_max_f32_e32 v134, v134, v181
	s_nop 1
	v_mov_b32_dpp v135, v134 row_ror:8 row_mask:0xf bank_mask:0xf
	s_nop 0
	v_max_f32_e32 v134, v134, v135
	ds_bpermute_b32 v135, v140, v134
	s_waitcnt lgkmcnt(0)
	v_max_f32_e32 v134, v134, v135
	ds_bpermute_b32 v135, v141, v134
	s_waitcnt lgkmcnt(0)
	v_max_f32_e32 v134, v134, v135
	v_mul_f32_e32 v134, 0xbfb8aa3b, v134
	v_fma_f32 v150, v150, s28, v134
	v_fma_f32 v151, v151, s28, v134
	v_fma_f32 v152, v152, s28, v134
	v_fma_f32 v153, v153, s28, v134
	v_fma_f32 v154, v154, s28, v134
	v_fma_f32 v155, v155, s28, v134
	v_fma_f32 v156, v156, s28, v134
	v_fma_f32 v157, v157, s28, v134
	v_fma_f32 v158, v158, s28, v134
	v_fma_f32 v159, v159, s28, v134
	v_fma_f32 v160, v160, s28, v134
	v_fma_f32 v161, v161, s28, v134
	v_fma_f32 v162, v162, s28, v134
	v_fma_f32 v163, v163, s28, v134
	v_fma_f32 v164, v164, s28, v134
	v_fma_f32 v165, v165, s28, v134
	v_fma_f32 v166, v166, s28, v134
	v_fma_f32 v167, v167, s28, v134
	v_fma_f32 v168, v168, s28, v134
	v_fma_f32 v169, v169, s28, v134
	v_fma_f32 v170, v170, s28, v134
	v_fma_f32 v171, v171, s28, v134
	v_fma_f32 v172, v172, s28, v134
	v_fma_f32 v173, v173, s28, v134
	v_fma_f32 v174, v174, s28, v134
	v_fma_f32 v175, v175, s28, v134
	v_fma_f32 v176, v176, s28, v134
	v_fma_f32 v177, v177, s28, v134
	v_fma_f32 v178, v178, s28, v134
	v_fma_f32 v179, v179, s28, v134
	v_fma_f32 v180, v180, s28, v134
	v_fma_f32 v181, v181, s28, v134
	v_exp_f32_e32 v150, v150
	v_exp_f32_e32 v151, v151
	v_exp_f32_e32 v152, v152
	v_exp_f32_e32 v153, v153
	v_exp_f32_e32 v154, v154
	v_exp_f32_e32 v155, v155
	v_exp_f32_e32 v156, v156
	v_exp_f32_e32 v157, v157
	v_exp_f32_e32 v158, v158
	v_exp_f32_e32 v159, v159
	v_exp_f32_e32 v160, v160
	v_exp_f32_e32 v161, v161
	v_exp_f32_e32 v162, v162
	v_exp_f32_e32 v163, v163
	v_exp_f32_e32 v164, v164
	v_exp_f32_e32 v165, v165
	v_exp_f32_e32 v166, v166
	v_exp_f32_e32 v167, v167
	v_exp_f32_e32 v168, v168
	v_exp_f32_e32 v169, v169
	v_exp_f32_e32 v170, v170
	v_exp_f32_e32 v171, v171
	v_exp_f32_e32 v172, v172
	v_exp_f32_e32 v173, v173
	v_exp_f32_e32 v174, v174
	v_exp_f32_e32 v175, v175
	v_exp_f32_e32 v176, v176
	v_exp_f32_e32 v177, v177
	v_exp_f32_e32 v178, v178
	v_exp_f32_e32 v179, v179
	v_exp_f32_e32 v180, v180
	v_exp_f32_e32 v181, v181
	s_nop 0
	v_add_f32_e32 v134, v150, v151
	v_add_f32_e32 v134, v134, v152
	v_add_f32_e32 v134, v134, v153
	v_add_f32_e32 v134, v134, v154
	v_add_f32_e32 v134, v134, v155
	v_add_f32_e32 v134, v134, v156
	v_add_f32_e32 v134, v134, v157
	v_add_f32_e32 v134, v134, v158
	v_add_f32_e32 v134, v134, v159
	v_add_f32_e32 v134, v134, v160
	v_add_f32_e32 v134, v134, v161
	v_add_f32_e32 v134, v134, v162
	v_add_f32_e32 v134, v134, v163
	v_add_f32_e32 v134, v134, v164
	v_add_f32_e32 v134, v134, v165
	v_add_f32_e32 v134, v134, v166
	v_add_f32_e32 v134, v134, v167
	v_add_f32_e32 v134, v134, v168
	v_add_f32_e32 v134, v134, v169
	v_add_f32_e32 v134, v134, v170
	v_add_f32_e32 v134, v134, v171
	v_add_f32_e32 v134, v134, v172
	v_add_f32_e32 v134, v134, v173
	v_add_f32_e32 v134, v134, v174
	v_add_f32_e32 v134, v134, v175
	v_add_f32_e32 v134, v134, v176
	v_add_f32_e32 v134, v134, v177
	v_add_f32_e32 v134, v134, v178
	v_add_f32_e32 v134, v134, v179
	v_add_f32_e32 v134, v134, v180
	v_add_f32_e32 v134, v134, v181
	s_nop 1
	v_mov_b32_dpp v135, v134 row_ror:8 row_mask:0xf bank_mask:0xf
	s_nop 0
	v_add_f32_e32 v134, v134, v135
	ds_bpermute_b32 v135, v140, v134
	s_waitcnt lgkmcnt(0)
	v_add_f32_e32 v134, v134, v135
	ds_bpermute_b32 v135, v141, v134
	s_waitcnt lgkmcnt(0)
	v_add_f32_e32 v134, v134, v135
	v_div_scale_f32 v132, s[8:9], v134, v134, 1.0
	v_rcp_f32_e32 v135, v132
	v_div_scale_f32 v133, vcc, 1.0, v134, 1.0
	v_fma_f32 v136, -v132, v135, 1.0
	v_fmac_f32_e32 v135, v136, v135
	v_mul_f32_e32 v136, v133, v135
	v_fma_f32 v137, -v132, v136, v133
	v_fmac_f32_e32 v136, v137, v135
	v_fma_f32 v132, -v132, v136, v133
	s_nop 1
	v_div_fmas_f32 v132, v132, v135, v136
	v_div_fixup_f32 v134, v132, v134, 1.0
	v_mov_b32_e32 v149, v134
	s_waitcnt vmcnt(31)
	ds_write_b32 v148, v240 offset:0
	ds_write_b32 v148, v241 offset:32
	ds_write_b32 v148, v242 offset:64
	ds_write_b32 v148, v243 offset:96
	v_cvt_pk_f32_fp8_e32 v[214:215], v0
	v_cvt_pk_f32_fp8_sdwa v[216:217], v0 src0_sel:WORD_1
	v_pk_mul_f32 v[198:199], v[150:151], v[214:215] op_sel_hi:[0,1]
	v_pk_mul_f32 v[200:201], v[150:151], v[216:217] op_sel_hi:[0,1]
	v_cvt_pk_f32_fp8_e32 v[218:219], v1
	v_cvt_pk_f32_fp8_sdwa v[220:221], v1 src0_sel:WORD_1
	v_pk_mul_f32 v[202:203], v[150:151], v[218:219] op_sel_hi:[0,1]
	v_pk_mul_f32 v[204:205], v[150:151], v[220:221] op_sel_hi:[0,1]
	v_cvt_pk_f32_fp8_e32 v[214:215], v2
	v_cvt_pk_f32_fp8_sdwa v[216:217], v2 src0_sel:WORD_1
	v_pk_mul_f32 v[206:207], v[150:151], v[214:215] op_sel_hi:[0,1]
	v_pk_mul_f32 v[208:209], v[150:151], v[216:217] op_sel_hi:[0,1]
	v_cvt_pk_f32_fp8_e32 v[218:219], v3
	v_cvt_pk_f32_fp8_sdwa v[220:221], v3 src0_sel:WORD_1
	v_pk_mul_f32 v[210:211], v[150:151], v[218:219] op_sel_hi:[0,1]
	v_pk_mul_f32 v[212:213], v[150:151], v[220:221] op_sel_hi:[0,1]
	s_waitcnt vmcnt(30)
; #define LAS __attribute__((address_space(3)))
; __device__ __forceinline__ void kv8_pv(const u32x4 (&buf)[8], f32x2v (&o2)[8], const LAS float* srow, int b) {
;     const LAS f32x4* p4 = (const LAS f32x4*)(srow + b * 8);
;     const f32x4 p0 = p4[0], p1 = p4[1];
;     const float p[8] = {p0.x, p0.y, p0.z, p0.w, p1.x, p1.y, p1.z, p1.w};
; #pragma unroll
;     for (int u = 0; u < 8; ++u) {
;         const u32x4 v = buf[u]; const f32x2v pp = {p[u], p[u]};
;         o2[0] = __builtin_elementwise_fma(pp, __builtin_amdgcn_cvt_pk_f32_fp8(v.x, false), o2[0]); o2[1] = __builtin_elementwise_fma(pp, __builtin_amdgcn_cvt_pk_f32_fp8(v.x, true), o2[1]);
;         o2[2] = __builtin_elementwise_fma(pp, __builtin_amdgcn_cvt_pk_f32_fp8(v.y, false), o2[2]); o2[3] = __builtin_elementwise_fma(pp, __builtin_amdgcn_cvt_pk_f32_fp8(v.y, true), o2[3]);
;         o2[4] = __builtin_elementwise_fma(pp, __builtin_amdgcn_cvt_pk_f32_fp8(v.z, false), o2[4]); o2[5] = __builtin_elementwise_fma(pp, __builtin_amdgcn_cvt_pk_f32_fp8(v.z, true), o2[5]);
;         o2[6] = __builtin_elementwise_fma(pp, __builtin_amdgcn_cvt_pk_f32_fp8(v.w, false), o2[6]); o2[7] = __builtin_elementwise_fma(pp, __builtin_amdgcn_cvt_pk_f32_fp8(v.w, true), o2[7]);
;     }
; __device__ __forceinline__ void attn_query8(const unsigned char* __restrict__ KV8, const bf16_t* __restrict__ Z, const int* __restrict__ SEL, bf16_t* __restrict__ YMIX, int t, LAS float* sbuf  ) {
;     ...
;         kv8_issue(C, rs, lvo, 0, iv, CLAMPB(b + 2));
;         kv8_qk(A, qf, srow, b, lane);
;         kv8_issue(A, rs, lvo, 0, iv, CLAMPB(b + 3));
	v_cvt_pk_f32_fp8_e32 v[214:215], v4
	v_cvt_pk_f32_fp8_sdwa v[216:217], v4 src0_sel:WORD_1
	v_pk_fma_f32 v[198:199], v[150:151], v[214:215], v[198:199] op_sel:[1,0,0]
	v_pk_fma_f32 v[200:201], v[150:151], v[216:217], v[200:201] op_sel:[1,0,0]
	v_cvt_pk_f32_fp8_e32 v[218:219], v5
	v_cvt_pk_f32_fp8_sdwa v[220:221], v5 src0_sel:WORD_1
	v_pk_fma_f32 v[202:203], v[150:151], v[218:219], v[202:203] op_sel:[1,0,0]
	v_pk_fma_f32 v[204:205], v[150:151], v[220:221], v[204:205] op_sel:[1,0,0]
	v_cvt_pk_f32_fp8_e32 v[214:215], v6
	v_cvt_pk_f32_fp8_sdwa v[216:217], v6 src0_sel:WORD_1
	v_pk_fma_f32 v[206:207], v[150:151], v[214:215], v[206:207] op_sel:[1,0,0]
	v_pk_fma_f32 v[208:209], v[150:151], v[216:217], v[208:209] op_sel:[1,0,0]
	v_cvt_pk_f32_fp8_e32 v[218:219], v7
	v_cvt_pk_f32_fp8_sdwa v[220:221], v7 src0_sel:WORD_1
	v_pk_fma_f32 v[210:211], v[150:151], v[218:219], v[210:211] op_sel:[1,0,0]
	v_pk_fma_f32 v[212:213], v[150:151], v[220:221], v[212:213] op_sel:[1,0,0]
	s_waitcnt vmcnt(29)
	v_cvt_pk_f32_fp8_e32 v[214:215], v8
	v_cvt_pk_f32_fp8_sdwa v[216:217], v8 src0_sel:WORD_1
	v_pk_fma_f32 v[198:199], v[152:153], v[214:215], v[198:199] op_sel_hi:[0,1,1]
	v_pk_fma_f32 v[200:201], v[152:153], v[216:217], v[200:201] op_sel_hi:[0,1,1]
	v_cvt_pk_f32_fp8_e32 v[218:219], v9
	v_cvt_pk_f32_fp8_sdwa v[220:221], v9 src0_sel:WORD_1
	v_pk_fma_f32 v[202:203], v[152:153], v[218:219], v[202:203] op_sel_hi:[0,1,1]
	v_pk_fma_f32 v[204:205], v[152:153], v[220:221], v[204:205] op_sel_hi:[0,1,1]
	v_cvt_pk_f32_fp8_e32 v[214:215], v10
	v_cvt_pk_f32_fp8_sdwa v[216:217], v10 src0_sel:WORD_1
	v_pk_fma_f32 v[206:207], v[152:153], v[214:215], v[206:207] op_sel_hi:[0,1,1]
	v_pk_fma_f32 v[208:209], v[152:153], v[216:217], v[208:209] op_sel_hi:[0,1,1]
	v_cvt_pk_f32_fp8_e32 v[218:219], v11
	v_cvt_pk_f32_fp8_sdwa v[220:221], v11 src0_sel:WORD_1
	v_pk_fma_f32 v[210:211], v[152:153], v[218:219], v[210:211] op_sel_hi:[0,1,1]
	v_pk_fma_f32 v[212:213], v[152:153], v[220:221], v[212:213] op_sel_hi:[0,1,1]
	s_waitcnt vmcnt(28)
	v_cvt_pk_f32_fp8_e32 v[214:215], v12
	v_cvt_pk_f32_fp8_sdwa v[216:217], v12 src0_sel:WORD_1
	v_pk_fma_f32 v[198:199], v[152:153], v[214:215], v[198:199] op_sel:[1,0,0]
	v_pk_fma_f32 v[200:201], v[152:153], v[216:217], v[200:201] op_sel:[1,0,0]
	v_cvt_pk_f32_fp8_e32 v[218:219], v13
	v_cvt_pk_f32_fp8_sdwa v[220:221], v13 src0_sel:WORD_1
	v_pk_fma_f32 v[202:203], v[152:153], v[218:219], v[202:203] op_sel:[1,0,0]
	v_pk_fma_f32 v[204:205], v[152:153], v[220:221], v[204:205] op_sel:[1,0,0]
	v_cvt_pk_f32_fp8_e32 v[214:215], v14
	v_cvt_pk_f32_fp8_sdwa v[216:217], v14 src0_sel:WORD_1
	v_pk_fma_f32 v[206:207], v[152:153], v[214:215], v[206:207] op_sel:[1,0,0]
	v_pk_fma_f32 v[208:209], v[152:153], v[216:217], v[208:209] op_sel:[1,0,0]
	v_cvt_pk_f32_fp8_e32 v[218:219], v15
	v_cvt_pk_f32_fp8_sdwa v[220:221], v15 src0_sel:WORD_1
	v_pk_fma_f32 v[210:211], v[152:153], v[218:219], v[210:211] op_sel:[1,0,0]
	v_pk_fma_f32 v[212:213], v[152:153], v[220:221], v[212:213] op_sel:[1,0,0]
	ds_read_b128 v[150:153], v139 offset:0
	s_waitcnt vmcnt(27)
	v_cvt_pk_f32_fp8_e32 v[214:215], v16
	v_cvt_pk_f32_fp8_sdwa v[216:217], v16 src0_sel:WORD_1
	v_pk_fma_f32 v[198:199], v[154:155], v[214:215], v[198:199] op_sel_hi:[0,1,1]
	v_pk_fma_f32 v[200:201], v[154:155], v[216:217], v[200:201] op_sel_hi:[0,1,1]
	v_cvt_pk_f32_fp8_e32 v[218:219], v17
	v_cvt_pk_f32_fp8_sdwa v[220:221], v17 src0_sel:WORD_1
	v_pk_fma_f32 v[202:203], v[154:155], v[218:219], v[202:203] op_sel_hi:[0,1,1]
	v_pk_fma_f32 v[204:205], v[154:155], v[220:221], v[204:205] op_sel_hi:[0,1,1]
	v_cvt_pk_f32_fp8_e32 v[214:215], v18
	v_cvt_pk_f32_fp8_sdwa v[216:217], v18 src0_sel:WORD_1
	v_pk_fma_f32 v[206:207], v[154:155], v[214:215], v[206:207] op_sel_hi:[0,1,1]
	v_pk_fma_f32 v[208:209], v[154:155], v[216:217], v[208:209] op_sel_hi:[0,1,1]
	v_cvt_pk_f32_fp8_e32 v[218:219], v19
	v_cvt_pk_f32_fp8_sdwa v[220:221], v19 src0_sel:WORD_1
	v_pk_fma_f32 v[210:211], v[154:155], v[218:219], v[210:211] op_sel_hi:[0,1,1]
	v_pk_fma_f32 v[212:213], v[154:155], v[220:221], v[212:213] op_sel_hi:[0,1,1]
	s_waitcnt vmcnt(26)
	v_cvt_pk_f32_fp8_e32 v[214:215], v20
	v_cvt_pk_f32_fp8_sdwa v[216:217], v20 src0_sel:WORD_1
	v_pk_fma_f32 v[198:199], v[154:155], v[214:215], v[198:199] op_sel:[1,0,0]
	v_pk_fma_f32 v[200:201], v[154:155], v[216:217], v[200:201] op_sel:[1,0,0]
	v_cvt_pk_f32_fp8_e32 v[218:219], v21
	v_cvt_pk_f32_fp8_sdwa v[220:221], v21 src0_sel:WORD_1
	v_pk_fma_f32 v[202:203], v[154:155], v[218:219], v[202:203] op_sel:[1,0,0]
	v_pk_fma_f32 v[204:205], v[154:155], v[220:221], v[204:205] op_sel:[1,0,0]
	v_cvt_pk_f32_fp8_e32 v[214:215], v22
	v_cvt_pk_f32_fp8_sdwa v[216:217], v22 src0_sel:WORD_1
	v_pk_fma_f32 v[206:207], v[154:155], v[214:215], v[206:207] op_sel:[1,0,0]
	v_pk_fma_f32 v[208:209], v[154:155], v[216:217], v[208:209] op_sel:[1,0,0]
	v_cvt_pk_f32_fp8_e32 v[218:219], v23
	v_cvt_pk_f32_fp8_sdwa v[220:221], v23 src0_sel:WORD_1
	v_pk_fma_f32 v[210:211], v[154:155], v[218:219], v[210:211] op_sel:[1,0,0]
	v_pk_fma_f32 v[212:213], v[154:155], v[220:221], v[212:213] op_sel:[1,0,0]
	s_waitcnt lgkmcnt(0)
	v_lshl_add_u32 v150, v150, 8, v138
	v_lshl_add_u32 v151, v151, 8, v138
	v_lshl_add_u32 v152, v152, 8, v138
	v_lshl_add_u32 v153, v153, 8, v138
	buffer_load_dwordx4 v[0:3], v150, s[16:19], s26 offen sc0
	buffer_load_dwordx4 v[4:7], v151, s[16:19], s26 offen sc0
	buffer_load_dwordx4 v[8:11], v152, s[16:19], s26 offen sc0
	buffer_load_dwordx4 v[12:15], v153, s[16:19], s26 offen sc0
	s_waitcnt vmcnt(29)
; #define LAS __attribute__((address_space(3)))
; __device__ __forceinline__ void kv8_pv(const u32x4 (&buf)[8], f32x2v (&o2)[8], const LAS float* srow, int b) {
;     const LAS f32x4* p4 = (const LAS f32x4*)(srow + b * 8);
;     const f32x4 p0 = p4[0], p1 = p4[1];
;     const float p[8] = {p0.x, p0.y, p0.z, p0.w, p1.x, p1.y, p1.z, p1.w};
; #pragma unroll
;     for (int u = 0; u < 8; ++u) {
;         const u32x4 v = buf[u]; const f32x2v pp = {p[u], p[u]};
;         o2[0] = __builtin_elementwise_fma(pp, __builtin_amdgcn_cvt_pk_f32_fp8(v.x, false), o2[0]); o2[1] = __builtin_elementwise_fma(pp, __builtin_amdgcn_cvt_pk_f32_fp8(v.x, true), o2[1]);
;         o2[2] = __builtin_elementwise_fma(pp, __builtin_amdgcn_cvt_pk_f32_fp8(v.y, false), o2[2]); o2[3] = __builtin_elementwise_fma(pp, __builtin_amdgcn_cvt_pk_f32_fp8(v.y, true), o2[3]);
;         o2[4] = __builtin_elementwise_fma(pp, __builtin_amdgcn_cvt_pk_f32_fp8(v.z, false), o2[4]); o2[5] = __builtin_elementwise_fma(pp, __builtin_amdgcn_cvt_pk_f32_fp8(v.z, true), o2[5]);
;         o2[6] = __builtin_elementwise_fma(pp, __builtin_amdgcn_cvt_pk_f32_fp8(v.w, false), o2[6]); o2[7] = __builtin_elementwise_fma(pp, __builtin_amdgcn_cvt_pk_f32_fp8(v.w, true), o2[7]);
;     }
; __device__ __forceinline__ void attn_query8(const unsigned char* __restrict__ KV8, const bf16_t* __restrict__ Z, const int* __restrict__ SEL, bf16_t* __restrict__ YMIX, int t, LAS float* sbuf  ) {
;     ...
;         kv8_issue(C, rs, lvo, 0, iv, CLAMPB(b + 2));
;         kv8_qk(A, qf, srow, b, lane);
;         kv8_issue(A, rs, lvo, 0, iv, CLAMPB(b + 3));
	v_cvt_pk_f32_fp8_e32 v[214:215], v24
	v_cvt_pk_f32_fp8_sdwa v[216:217], v24 src0_sel:WORD_1
	v_pk_fma_f32 v[198:199], v[156:157], v[214:215], v[198:199] op_sel_hi:[0,1,1]
	v_pk_fma_f32 v[200:201], v[156:157], v[216:217], v[200:201] op_sel_hi:[0,1,1]
	v_cvt_pk_f32_fp8_e32 v[218:219], v25
	v_cvt_pk_f32_fp8_sdwa v[220:221], v25 src0_sel:WORD_1
	v_pk_fma_f32 v[202:203], v[156:157], v[218:219], v[202:203] op_sel_hi:[0,1,1]
	v_pk_fma_f32 v[204:205], v[156:157], v[220:221], v[204:205] op_sel_hi:[0,1,1]
	v_cvt_pk_f32_fp8_e32 v[214:215], v26
	v_cvt_pk_f32_fp8_sdwa v[216:217], v26 src0_sel:WORD_1
	v_pk_fma_f32 v[206:207], v[156:157], v[214:215], v[206:207] op_sel_hi:[0,1,1]
	v_pk_fma_f32 v[208:209], v[156:157], v[216:217], v[208:209] op_sel_hi:[0,1,1]
	v_cvt_pk_f32_fp8_e32 v[218:219], v27
	v_cvt_pk_f32_fp8_sdwa v[220:221], v27 src0_sel:WORD_1
	v_pk_fma_f32 v[210:211], v[156:157], v[218:219], v[210:211] op_sel_hi:[0,1,1]
	v_pk_fma_f32 v[212:213], v[156:157], v[220:221], v[212:213] op_sel_hi:[0,1,1]
	s_waitcnt vmcnt(28)
	v_cvt_pk_f32_fp8_e32 v[214:215], v28
	v_cvt_pk_f32_fp8_sdwa v[216:217], v28 src0_sel:WORD_1
	v_pk_fma_f32 v[198:199], v[156:157], v[214:215], v[198:199] op_sel:[1,0,0]
	v_pk_fma_f32 v[200:201], v[156:157], v[216:217], v[200:201] op_sel:[1,0,0]
	v_cvt_pk_f32_fp8_e32 v[218:219], v29
	v_cvt_pk_f32_fp8_sdwa v[220:221], v29 src0_sel:WORD_1
	v_pk_fma_f32 v[202:203], v[156:157], v[218:219], v[202:203] op_sel:[1,0,0]
	v_pk_fma_f32 v[204:205], v[156:157], v[220:221], v[204:205] op_sel:[1,0,0]
	v_cvt_pk_f32_fp8_e32 v[214:215], v30
	v_cvt_pk_f32_fp8_sdwa v[216:217], v30 src0_sel:WORD_1
	v_pk_fma_f32 v[206:207], v[156:157], v[214:215], v[206:207] op_sel:[1,0,0]
	v_pk_fma_f32 v[208:209], v[156:157], v[216:217], v[208:209] op_sel:[1,0,0]
	v_cvt_pk_f32_fp8_e32 v[218:219], v31
	v_cvt_pk_f32_fp8_sdwa v[220:221], v31 src0_sel:WORD_1
	v_pk_fma_f32 v[210:211], v[156:157], v[218:219], v[210:211] op_sel:[1,0,0]
	v_pk_fma_f32 v[212:213], v[156:157], v[220:221], v[212:213] op_sel:[1,0,0]
	ds_read_b128 v[154:157], v139 offset:16
	s_waitcnt vmcnt(27)
	v_cvt_pk_f32_fp8_e32 v[214:215], v32
	v_cvt_pk_f32_fp8_sdwa v[216:217], v32 src0_sel:WORD_1
	v_pk_fma_f32 v[198:199], v[158:159], v[214:215], v[198:199] op_sel_hi:[0,1,1]
	v_pk_fma_f32 v[200:201], v[158:159], v[216:217], v[200:201] op_sel_hi:[0,1,1]
	v_cvt_pk_f32_fp8_e32 v[218:219], v33
	v_cvt_pk_f32_fp8_sdwa v[220:221], v33 src0_sel:WORD_1
	v_pk_fma_f32 v[202:203], v[158:159], v[218:219], v[202:203] op_sel_hi:[0,1,1]
	v_pk_fma_f32 v[204:205], v[158:159], v[220:221], v[204:205] op_sel_hi:[0,1,1]
	v_cvt_pk_f32_fp8_e32 v[214:215], v34
	v_cvt_pk_f32_fp8_sdwa v[216:217], v34 src0_sel:WORD_1
	v_pk_fma_f32 v[206:207], v[158:159], v[214:215], v[206:207] op_sel_hi:[0,1,1]
	v_pk_fma_f32 v[208:209], v[158:159], v[216:217], v[208:209] op_sel_hi:[0,1,1]
	v_cvt_pk_f32_fp8_e32 v[218:219], v35
	v_cvt_pk_f32_fp8_sdwa v[220:221], v35 src0_sel:WORD_1
	v_pk_fma_f32 v[210:211], v[158:159], v[218:219], v[210:211] op_sel_hi:[0,1,1]
	v_pk_fma_f32 v[212:213], v[158:159], v[220:221], v[212:213] op_sel_hi:[0,1,1]
	s_waitcnt vmcnt(26)
	v_cvt_pk_f32_fp8_e32 v[214:215], v36
	v_cvt_pk_f32_fp8_sdwa v[216:217], v36 src0_sel:WORD_1
	v_pk_fma_f32 v[198:199], v[158:159], v[214:215], v[198:199] op_sel:[1,0,0]
	v_pk_fma_f32 v[200:201], v[158:159], v[216:217], v[200:201] op_sel:[1,0,0]
	v_cvt_pk_f32_fp8_e32 v[218:219], v37
	v_cvt_pk_f32_fp8_sdwa v[220:221], v37 src0_sel:WORD_1
	v_pk_fma_f32 v[202:203], v[158:159], v[218:219], v[202:203] op_sel:[1,0,0]
	v_pk_fma_f32 v[204:205], v[158:159], v[220:221], v[204:205] op_sel:[1,0,0]
	v_cvt_pk_f32_fp8_e32 v[214:215], v38
	v_cvt_pk_f32_fp8_sdwa v[216:217], v38 src0_sel:WORD_1
	v_pk_fma_f32 v[206:207], v[158:159], v[214:215], v[206:207] op_sel:[1,0,0]
	v_pk_fma_f32 v[208:209], v[158:159], v[216:217], v[208:209] op_sel:[1,0,0]
	v_cvt_pk_f32_fp8_e32 v[218:219], v39
	v_cvt_pk_f32_fp8_sdwa v[220:221], v39 src0_sel:WORD_1
	v_pk_fma_f32 v[210:211], v[158:159], v[218:219], v[210:211] op_sel:[1,0,0]
	v_pk_fma_f32 v[212:213], v[158:159], v[220:221], v[212:213] op_sel:[1,0,0]
	s_waitcnt lgkmcnt(0)
	v_lshl_add_u32 v154, v154, 8, v138
	v_lshl_add_u32 v155, v155, 8, v138
	v_lshl_add_u32 v156, v156, 8, v138
	v_lshl_add_u32 v157, v157, 8, v138
	buffer_load_dwordx4 v[16:19], v154, s[16:19], s26 offen sc0
	buffer_load_dwordx4 v[20:23], v155, s[16:19], s26 offen sc0
	buffer_load_dwordx4 v[24:27], v156, s[16:19], s26 offen sc0
	buffer_load_dwordx4 v[28:31], v157, s[16:19], s26 offen sc0
	s_waitcnt vmcnt(29)
	v_cvt_pk_f32_fp8_e32 v[214:215], v40
	v_cvt_pk_f32_fp8_sdwa v[216:217], v40 src0_sel:WORD_1
	v_pk_fma_f32 v[198:199], v[160:161], v[214:215], v[198:199] op_sel_hi:[0,1,1]
	v_pk_fma_f32 v[200:201], v[160:161], v[216:217], v[200:201] op_sel_hi:[0,1,1]
	v_cvt_pk_f32_fp8_e32 v[218:219], v41
	v_cvt_pk_f32_fp8_sdwa v[220:221], v41 src0_sel:WORD_1
	v_pk_fma_f32 v[202:203], v[160:161], v[218:219], v[202:203] op_sel_hi:[0,1,1]
	v_pk_fma_f32 v[204:205], v[160:161], v[220:221], v[204:205] op_sel_hi:[0,1,1]
	v_cvt_pk_f32_fp8_e32 v[214:215], v42
	v_cvt_pk_f32_fp8_sdwa v[216:217], v42 src0_sel:WORD_1
	v_pk_fma_f32 v[206:207], v[160:161], v[214:215], v[206:207] op_sel_hi:[0,1,1]
	v_pk_fma_f32 v[208:209], v[160:161], v[216:217], v[208:209] op_sel_hi:[0,1,1]
	v_cvt_pk_f32_fp8_e32 v[218:219], v43
	v_cvt_pk_f32_fp8_sdwa v[220:221], v43 src0_sel:WORD_1
	v_pk_fma_f32 v[210:211], v[160:161], v[218:219], v[210:211] op_sel_hi:[0,1,1]
	v_pk_fma_f32 v[212:213], v[160:161], v[220:221], v[212:213] op_sel_hi:[0,1,1]
	s_waitcnt vmcnt(28)
; #define LAS __attribute__((address_space(3)))
; __device__ __forceinline__ void kv8_pv(const u32x4 (&buf)[8], f32x2v (&o2)[8], const LAS float* srow, int b) {
;     const LAS f32x4* p4 = (const LAS f32x4*)(srow + b * 8);
;     const f32x4 p0 = p4[0], p1 = p4[1];
;     const float p[8] = {p0.x, p0.y, p0.z, p0.w, p1.x, p1.y, p1.z, p1.w};
; #pragma unroll
;     for (int u = 0; u < 8; ++u) {
;         const u32x4 v = buf[u]; const f32x2v pp = {p[u], p[u]};
;         o2[0] = __builtin_elementwise_fma(pp, __builtin_amdgcn_cvt_pk_f32_fp8(v.x, false), o2[0]); o2[1] = __builtin_elementwise_fma(pp, __builtin_amdgcn_cvt_pk_f32_fp8(v.x, true), o2[1]);
;         o2[2] = __builtin_elementwise_fma(pp, __builtin_amdgcn_cvt_pk_f32_fp8(v.y, false), o2[2]); o2[3] = __builtin_elementwise_fma(pp, __builtin_amdgcn_cvt_pk_f32_fp8(v.y, true), o2[3]);
;         o2[4] = __builtin_elementwise_fma(pp, __builtin_amdgcn_cvt_pk_f32_fp8(v.z, false), o2[4]); o2[5] = __builtin_elementwise_fma(pp, __builtin_amdgcn_cvt_pk_f32_fp8(v.z, true), o2[5]);
;         o2[6] = __builtin_elementwise_fma(pp, __builtin_amdgcn_cvt_pk_f32_fp8(v.w, false), o2[6]); o2[7] = __builtin_elementwise_fma(pp, __builtin_amdgcn_cvt_pk_f32_fp8(v.w, true), o2[7]);
;     }
; __device__ __forceinline__ void attn_query8(const unsigned char* __restrict__ KV8, const bf16_t* __restrict__ Z, const int* __restrict__ SEL, bf16_t* __restrict__ YMIX, int t, LAS float* sbuf  ) {
;     ...
;         kv8_issue(C, rs, lvo, 0, iv, CLAMPB(b + 2));
;         kv8_qk(A, qf, srow, b, lane);
;         kv8_issue(A, rs, lvo, 0, iv, CLAMPB(b + 3));
	v_cvt_pk_f32_fp8_e32 v[214:215], v44
	v_cvt_pk_f32_fp8_sdwa v[216:217], v44 src0_sel:WORD_1
	v_pk_fma_f32 v[198:199], v[160:161], v[214:215], v[198:199] op_sel:[1,0,0]
	v_pk_fma_f32 v[200:201], v[160:161], v[216:217], v[200:201] op_sel:[1,0,0]
	v_cvt_pk_f32_fp8_e32 v[218:219], v45
	v_cvt_pk_f32_fp8_sdwa v[220:221], v45 src0_sel:WORD_1
	v_pk_fma_f32 v[202:203], v[160:161], v[218:219], v[202:203] op_sel:[1,0,0]
	v_pk_fma_f32 v[204:205], v[160:161], v[220:221], v[204:205] op_sel:[1,0,0]
	v_cvt_pk_f32_fp8_e32 v[214:215], v46
	v_cvt_pk_f32_fp8_sdwa v[216:217], v46 src0_sel:WORD_1
	v_pk_fma_f32 v[206:207], v[160:161], v[214:215], v[206:207] op_sel:[1,0,0]
	v_pk_fma_f32 v[208:209], v[160:161], v[216:217], v[208:209] op_sel:[1,0,0]
	v_cvt_pk_f32_fp8_e32 v[218:219], v47
	v_cvt_pk_f32_fp8_sdwa v[220:221], v47 src0_sel:WORD_1
	v_pk_fma_f32 v[210:211], v[160:161], v[218:219], v[210:211] op_sel:[1,0,0]
	v_pk_fma_f32 v[212:213], v[160:161], v[220:221], v[212:213] op_sel:[1,0,0]
	ds_read_b128 v[158:161], v139 offset:32
	s_waitcnt vmcnt(27)
	v_cvt_pk_f32_fp8_e32 v[214:215], v48
	v_cvt_pk_f32_fp8_sdwa v[216:217], v48 src0_sel:WORD_1
	v_pk_fma_f32 v[198:199], v[162:163], v[214:215], v[198:199] op_sel_hi:[0,1,1]
	v_pk_fma_f32 v[200:201], v[162:163], v[216:217], v[200:201] op_sel_hi:[0,1,1]
	v_cvt_pk_f32_fp8_e32 v[218:219], v49
	v_cvt_pk_f32_fp8_sdwa v[220:221], v49 src0_sel:WORD_1
	v_pk_fma_f32 v[202:203], v[162:163], v[218:219], v[202:203] op_sel_hi:[0,1,1]
	v_pk_fma_f32 v[204:205], v[162:163], v[220:221], v[204:205] op_sel_hi:[0,1,1]
	v_cvt_pk_f32_fp8_e32 v[214:215], v50
	v_cvt_pk_f32_fp8_sdwa v[216:217], v50 src0_sel:WORD_1
	v_pk_fma_f32 v[206:207], v[162:163], v[214:215], v[206:207] op_sel_hi:[0,1,1]
	v_pk_fma_f32 v[208:209], v[162:163], v[216:217], v[208:209] op_sel_hi:[0,1,1]
	v_cvt_pk_f32_fp8_e32 v[218:219], v51
	v_cvt_pk_f32_fp8_sdwa v[220:221], v51 src0_sel:WORD_1
	v_pk_fma_f32 v[210:211], v[162:163], v[218:219], v[210:211] op_sel_hi:[0,1,1]
	v_pk_fma_f32 v[212:213], v[162:163], v[220:221], v[212:213] op_sel_hi:[0,1,1]
	s_waitcnt vmcnt(26)
	v_cvt_pk_f32_fp8_e32 v[214:215], v52
	v_cvt_pk_f32_fp8_sdwa v[216:217], v52 src0_sel:WORD_1
	v_pk_fma_f32 v[198:199], v[162:163], v[214:215], v[198:199] op_sel:[1,0,0]
	v_pk_fma_f32 v[200:201], v[162:163], v[216:217], v[200:201] op_sel:[1,0,0]
	v_cvt_pk_f32_fp8_e32 v[218:219], v53
	v_cvt_pk_f32_fp8_sdwa v[220:221], v53 src0_sel:WORD_1
	v_pk_fma_f32 v[202:203], v[162:163], v[218:219], v[202:203] op_sel:[1,0,0]
	v_pk_fma_f32 v[204:205], v[162:163], v[220:221], v[204:205] op_sel:[1,0,0]
	v_cvt_pk_f32_fp8_e32 v[214:215], v54
	v_cvt_pk_f32_fp8_sdwa v[216:217], v54 src0_sel:WORD_1
	v_pk_fma_f32 v[206:207], v[162:163], v[214:215], v[206:207] op_sel:[1,0,0]
	v_pk_fma_f32 v[208:209], v[162:163], v[216:217], v[208:209] op_sel:[1,0,0]
	v_cvt_pk_f32_fp8_e32 v[218:219], v55
	v_cvt_pk_f32_fp8_sdwa v[220:221], v55 src0_sel:WORD_1
	v_pk_fma_f32 v[210:211], v[162:163], v[218:219], v[210:211] op_sel:[1,0,0]
	v_pk_fma_f32 v[212:213], v[162:163], v[220:221], v[212:213] op_sel:[1,0,0]
	s_waitcnt lgkmcnt(0)
	v_lshl_add_u32 v158, v158, 8, v138
	v_lshl_add_u32 v159, v159, 8, v138
	v_lshl_add_u32 v160, v160, 8, v138
	v_lshl_add_u32 v161, v161, 8, v138
	buffer_load_dwordx4 v[32:35], v158, s[16:19], s26 offen sc0
	buffer_load_dwordx4 v[36:39], v159, s[16:19], s26 offen sc0
	buffer_load_dwordx4 v[40:43], v160, s[16:19], s26 offen sc0
	buffer_load_dwordx4 v[44:47], v161, s[16:19], s26 offen sc0
	s_waitcnt vmcnt(29)
	v_cvt_pk_f32_fp8_e32 v[214:215], v56
	v_cvt_pk_f32_fp8_sdwa v[216:217], v56 src0_sel:WORD_1
	v_pk_fma_f32 v[198:199], v[164:165], v[214:215], v[198:199] op_sel_hi:[0,1,1]
	v_pk_fma_f32 v[200:201], v[164:165], v[216:217], v[200:201] op_sel_hi:[0,1,1]
	v_cvt_pk_f32_fp8_e32 v[218:219], v57
	v_cvt_pk_f32_fp8_sdwa v[220:221], v57 src0_sel:WORD_1
	v_pk_fma_f32 v[202:203], v[164:165], v[218:219], v[202:203] op_sel_hi:[0,1,1]
	v_pk_fma_f32 v[204:205], v[164:165], v[220:221], v[204:205] op_sel_hi:[0,1,1]
	v_cvt_pk_f32_fp8_e32 v[214:215], v58
	v_cvt_pk_f32_fp8_sdwa v[216:217], v58 src0_sel:WORD_1
	v_pk_fma_f32 v[206:207], v[164:165], v[214:215], v[206:207] op_sel_hi:[0,1,1]
	v_pk_fma_f32 v[208:209], v[164:165], v[216:217], v[208:209] op_sel_hi:[0,1,1]
	v_cvt_pk_f32_fp8_e32 v[218:219], v59
	v_cvt_pk_f32_fp8_sdwa v[220:221], v59 src0_sel:WORD_1
	v_pk_fma_f32 v[210:211], v[164:165], v[218:219], v[210:211] op_sel_hi:[0,1,1]
	v_pk_fma_f32 v[212:213], v[164:165], v[220:221], v[212:213] op_sel_hi:[0,1,1]
	s_waitcnt vmcnt(28)
	v_cvt_pk_f32_fp8_e32 v[214:215], v60
	v_cvt_pk_f32_fp8_sdwa v[216:217], v60 src0_sel:WORD_1
	v_pk_fma_f32 v[198:199], v[164:165], v[214:215], v[198:199] op_sel:[1,0,0]
	v_pk_fma_f32 v[200:201], v[164:165], v[216:217], v[200:201] op_sel:[1,0,0]
	v_cvt_pk_f32_fp8_e32 v[218:219], v61
	v_cvt_pk_f32_fp8_sdwa v[220:221], v61 src0_sel:WORD_1
	v_pk_fma_f32 v[202:203], v[164:165], v[218:219], v[202:203] op_sel:[1,0,0]
	v_pk_fma_f32 v[204:205], v[164:165], v[220:221], v[204:205] op_sel:[1,0,0]
	v_cvt_pk_f32_fp8_e32 v[214:215], v62
	v_cvt_pk_f32_fp8_sdwa v[216:217], v62 src0_sel:WORD_1
	v_pk_fma_f32 v[206:207], v[164:165], v[214:215], v[206:207] op_sel:[1,0,0]
	v_pk_fma_f32 v[208:209], v[164:165], v[216:217], v[208:209] op_sel:[1,0,0]
	v_cvt_pk_f32_fp8_e32 v[218:219], v63
	v_cvt_pk_f32_fp8_sdwa v[220:221], v63 src0_sel:WORD_1
	v_pk_fma_f32 v[210:211], v[164:165], v[218:219], v[210:211] op_sel:[1,0,0]
	v_pk_fma_f32 v[212:213], v[164:165], v[220:221], v[212:213] op_sel:[1,0,0]
	ds_read_b128 v[162:165], v139 offset:48
	s_waitcnt vmcnt(27)
; #define LAS __attribute__((address_space(3)))
; __device__ __forceinline__ void kv8_issue(u32x4 (&buf)[8], __amdgpu_buffer_rsrc_t rs, int voff  , int sbase  , const int (&iv)[4], int b) {
;     const int jj = b >> 3, l0 = (b & 7) * 8;
;     const int ivb = (jj == 0) ? iv[0] : (jj == 1) ? iv[1] : (jj == 2) ? iv[2] : iv[3];
; #pragma unroll
;     for (int u = 0; u < 8; ++u) { const int si = __builtin_amdgcn_readlane(ivb, l0 + u); buf[u] = __builtin_amdgcn_raw_buffer_load_b128(rs, voff, si * 2048 + sbase, KV8_AUX); }
; }
; __device__ __forceinline__ void kv8_pv(const u32x4 (&buf)[8], f32x2v (&o2)[8], const LAS float* srow, int b) {
;     const LAS f32x4* p4 = (const LAS f32x4*)(srow + b * 8);
;     const f32x4 p0 = p4[0], p1 = p4[1];
;     const float p[8] = {p0.x, p0.y, p0.z, p0.w, p1.x, p1.y, p1.z, p1.w};
; #pragma unroll
;     for (int u = 0; u < 8; ++u) {
;         const u32x4 v = buf[u]; const f32x2v pp = {p[u], p[u]};
;         o2[0] = __builtin_elementwise_fma(pp, __builtin_amdgcn_cvt_pk_f32_fp8(v.x, false), o2[0]); o2[1] = __builtin_elementwise_fma(pp, __builtin_amdgcn_cvt_pk_f32_fp8(v.x, true), o2[1]);
;         o2[2] = __builtin_elementwise_fma(pp, __builtin_amdgcn_cvt_pk_f32_fp8(v.y, false), o2[2]); o2[3] = __builtin_elementwise_fma(pp, __builtin_amdgcn_cvt_pk_f32_fp8(v.y, true), o2[3]);
;         o2[4] = __builtin_elementwise_fma(pp, __builtin_amdgcn_cvt_pk_f32_fp8(v.z, false), o2[4]); o2[5] = __builtin_elementwise_fma(pp, __builtin_amdgcn_cvt_pk_f32_fp8(v.z, true), o2[5]);
;         o2[6] = __builtin_elementwise_fma(pp, __builtin_amdgcn_cvt_pk_f32_fp8(v.w, false), o2[6]); o2[7] = __builtin_elementwise_fma(pp, __builtin_amdgcn_cvt_pk_f32_fp8(v.w, true), o2[7]);
;     }
; }
	v_cvt_pk_f32_fp8_e32 v[214:215], v64
	v_cvt_pk_f32_fp8_sdwa v[216:217], v64 src0_sel:WORD_1
	v_pk_fma_f32 v[198:199], v[166:167], v[214:215], v[198:199] op_sel_hi:[0,1,1]
	v_pk_fma_f32 v[200:201], v[166:167], v[216:217], v[200:201] op_sel_hi:[0,1,1]
	v_cvt_pk_f32_fp8_e32 v[218:219], v65
	v_cvt_pk_f32_fp8_sdwa v[220:221], v65 src0_sel:WORD_1
	v_pk_fma_f32 v[202:203], v[166:167], v[218:219], v[202:203] op_sel_hi:[0,1,1]
	v_pk_fma_f32 v[204:205], v[166:167], v[220:221], v[204:205] op_sel_hi:[0,1,1]
	v_cvt_pk_f32_fp8_e32 v[214:215], v66
	v_cvt_pk_f32_fp8_sdwa v[216:217], v66 src0_sel:WORD_1
	v_pk_fma_f32 v[206:207], v[166:167], v[214:215], v[206:207] op_sel_hi:[0,1,1]
	v_pk_fma_f32 v[208:209], v[166:167], v[216:217], v[208:209] op_sel_hi:[0,1,1]
	v_cvt_pk_f32_fp8_e32 v[218:219], v67
	v_cvt_pk_f32_fp8_sdwa v[220:221], v67 src0_sel:WORD_1
	v_pk_fma_f32 v[210:211], v[166:167], v[218:219], v[210:211] op_sel_hi:[0,1,1]
	v_pk_fma_f32 v[212:213], v[166:167], v[220:221], v[212:213] op_sel_hi:[0,1,1]
	s_waitcnt vmcnt(26)
	v_cvt_pk_f32_fp8_e32 v[214:215], v68
	v_cvt_pk_f32_fp8_sdwa v[216:217], v68 src0_sel:WORD_1
	v_pk_fma_f32 v[198:199], v[166:167], v[214:215], v[198:199] op_sel:[1,0,0]
	v_pk_fma_f32 v[200:201], v[166:167], v[216:217], v[200:201] op_sel:[1,0,0]
	v_cvt_pk_f32_fp8_e32 v[218:219], v69
	v_cvt_pk_f32_fp8_sdwa v[220:221], v69 src0_sel:WORD_1
	v_pk_fma_f32 v[202:203], v[166:167], v[218:219], v[202:203] op_sel:[1,0,0]
	v_pk_fma_f32 v[204:205], v[166:167], v[220:221], v[204:205] op_sel:[1,0,0]
	v_cvt_pk_f32_fp8_e32 v[214:215], v70
	v_cvt_pk_f32_fp8_sdwa v[216:217], v70 src0_sel:WORD_1
	v_pk_fma_f32 v[206:207], v[166:167], v[214:215], v[206:207] op_sel:[1,0,0]
	v_pk_fma_f32 v[208:209], v[166:167], v[216:217], v[208:209] op_sel:[1,0,0]
	v_cvt_pk_f32_fp8_e32 v[218:219], v71
	v_cvt_pk_f32_fp8_sdwa v[220:221], v71 src0_sel:WORD_1
	v_pk_fma_f32 v[210:211], v[166:167], v[218:219], v[210:211] op_sel:[1,0,0]
	v_pk_fma_f32 v[212:213], v[166:167], v[220:221], v[212:213] op_sel:[1,0,0]
	s_waitcnt lgkmcnt(0)
	v_lshl_add_u32 v162, v162, 8, v138
	v_lshl_add_u32 v163, v163, 8, v138
	v_lshl_add_u32 v164, v164, 8, v138
	v_lshl_add_u32 v165, v165, 8, v138
	buffer_load_dwordx4 v[48:51], v162, s[16:19], s26 offen sc0
	buffer_load_dwordx4 v[52:55], v163, s[16:19], s26 offen sc0
	buffer_load_dwordx4 v[56:59], v164, s[16:19], s26 offen sc0
	buffer_load_dwordx4 v[60:63], v165, s[16:19], s26 offen sc0
	s_waitcnt vmcnt(29)
	v_cvt_pk_f32_fp8_e32 v[214:215], v72
	v_cvt_pk_f32_fp8_sdwa v[216:217], v72 src0_sel:WORD_1
	v_pk_fma_f32 v[198:199], v[168:169], v[214:215], v[198:199] op_sel_hi:[0,1,1]
	v_pk_fma_f32 v[200:201], v[168:169], v[216:217], v[200:201] op_sel_hi:[0,1,1]
	v_cvt_pk_f32_fp8_e32 v[218:219], v73
	v_cvt_pk_f32_fp8_sdwa v[220:221], v73 src0_sel:WORD_1
	v_pk_fma_f32 v[202:203], v[168:169], v[218:219], v[202:203] op_sel_hi:[0,1,1]
	v_pk_fma_f32 v[204:205], v[168:169], v[220:221], v[204:205] op_sel_hi:[0,1,1]
	v_cvt_pk_f32_fp8_e32 v[214:215], v74
	v_cvt_pk_f32_fp8_sdwa v[216:217], v74 src0_sel:WORD_1
	v_pk_fma_f32 v[206:207], v[168:169], v[214:215], v[206:207] op_sel_hi:[0,1,1]
	v_pk_fma_f32 v[208:209], v[168:169], v[216:217], v[208:209] op_sel_hi:[0,1,1]
	v_cvt_pk_f32_fp8_e32 v[218:219], v75
	v_cvt_pk_f32_fp8_sdwa v[220:221], v75 src0_sel:WORD_1
	v_pk_fma_f32 v[210:211], v[168:169], v[218:219], v[210:211] op_sel_hi:[0,1,1]
	v_pk_fma_f32 v[212:213], v[168:169], v[220:221], v[212:213] op_sel_hi:[0,1,1]
	s_waitcnt vmcnt(28)
	v_cvt_pk_f32_fp8_e32 v[214:215], v76
	v_cvt_pk_f32_fp8_sdwa v[216:217], v76 src0_sel:WORD_1
	v_pk_fma_f32 v[198:199], v[168:169], v[214:215], v[198:199] op_sel:[1,0,0]
	v_pk_fma_f32 v[200:201], v[168:169], v[216:217], v[200:201] op_sel:[1,0,0]
	v_cvt_pk_f32_fp8_e32 v[218:219], v77
	v_cvt_pk_f32_fp8_sdwa v[220:221], v77 src0_sel:WORD_1
	v_pk_fma_f32 v[202:203], v[168:169], v[218:219], v[202:203] op_sel:[1,0,0]
	v_pk_fma_f32 v[204:205], v[168:169], v[220:221], v[204:205] op_sel:[1,0,0]
	v_cvt_pk_f32_fp8_e32 v[214:215], v78
	v_cvt_pk_f32_fp8_sdwa v[216:217], v78 src0_sel:WORD_1
	v_pk_fma_f32 v[206:207], v[168:169], v[214:215], v[206:207] op_sel:[1,0,0]
	v_pk_fma_f32 v[208:209], v[168:169], v[216:217], v[208:209] op_sel:[1,0,0]
	v_cvt_pk_f32_fp8_e32 v[218:219], v79
	v_cvt_pk_f32_fp8_sdwa v[220:221], v79 src0_sel:WORD_1
	v_pk_fma_f32 v[210:211], v[168:169], v[218:219], v[210:211] op_sel:[1,0,0]
	v_pk_fma_f32 v[212:213], v[168:169], v[220:221], v[212:213] op_sel:[1,0,0]
	ds_read_b128 v[166:169], v139 offset:64
	s_waitcnt vmcnt(27)
	v_cvt_pk_f32_fp8_e32 v[214:215], v80
	v_cvt_pk_f32_fp8_sdwa v[216:217], v80 src0_sel:WORD_1
	v_pk_fma_f32 v[198:199], v[170:171], v[214:215], v[198:199] op_sel_hi:[0,1,1]
	v_pk_fma_f32 v[200:201], v[170:171], v[216:217], v[200:201] op_sel_hi:[0,1,1]
	v_cvt_pk_f32_fp8_e32 v[218:219], v81
	v_cvt_pk_f32_fp8_sdwa v[220:221], v81 src0_sel:WORD_1
	v_pk_fma_f32 v[202:203], v[170:171], v[218:219], v[202:203] op_sel_hi:[0,1,1]
	v_pk_fma_f32 v[204:205], v[170:171], v[220:221], v[204:205] op_sel_hi:[0,1,1]
	v_cvt_pk_f32_fp8_e32 v[214:215], v82
	v_cvt_pk_f32_fp8_sdwa v[216:217], v82 src0_sel:WORD_1
	v_pk_fma_f32 v[206:207], v[170:171], v[214:215], v[206:207] op_sel_hi:[0,1,1]
	v_pk_fma_f32 v[208:209], v[170:171], v[216:217], v[208:209] op_sel_hi:[0,1,1]
	v_cvt_pk_f32_fp8_e32 v[218:219], v83
	v_cvt_pk_f32_fp8_sdwa v[220:221], v83 src0_sel:WORD_1
	v_pk_fma_f32 v[210:211], v[170:171], v[218:219], v[210:211] op_sel_hi:[0,1,1]
	v_pk_fma_f32 v[212:213], v[170:171], v[220:221], v[212:213] op_sel_hi:[0,1,1]
	s_waitcnt vmcnt(26)
; #define LAS __attribute__((address_space(3)))
; __device__ __forceinline__ void kv8_issue(u32x4 (&buf)[8], __amdgpu_buffer_rsrc_t rs, int voff  , int sbase  , const int (&iv)[4], int b) {
;     const int jj = b >> 3, l0 = (b & 7) * 8;
;     const int ivb = (jj == 0) ? iv[0] : (jj == 1) ? iv[1] : (jj == 2) ? iv[2] : iv[3];
; #pragma unroll
;     for (int u = 0; u < 8; ++u) { const int si = __builtin_amdgcn_readlane(ivb, l0 + u); buf[u] = __builtin_amdgcn_raw_buffer_load_b128(rs, voff, si * 2048 + sbase, KV8_AUX); }
; }
; __device__ __forceinline__ void kv8_pv(const u32x4 (&buf)[8], f32x2v (&o2)[8], const LAS float* srow, int b) {
;     const LAS f32x4* p4 = (const LAS f32x4*)(srow + b * 8);
;     const f32x4 p0 = p4[0], p1 = p4[1];
;     const float p[8] = {p0.x, p0.y, p0.z, p0.w, p1.x, p1.y, p1.z, p1.w};
; #pragma unroll
;     for (int u = 0; u < 8; ++u) {
;         const u32x4 v = buf[u]; const f32x2v pp = {p[u], p[u]};
;         o2[0] = __builtin_elementwise_fma(pp, __builtin_amdgcn_cvt_pk_f32_fp8(v.x, false), o2[0]); o2[1] = __builtin_elementwise_fma(pp, __builtin_amdgcn_cvt_pk_f32_fp8(v.x, true), o2[1]);
;         o2[2] = __builtin_elementwise_fma(pp, __builtin_amdgcn_cvt_pk_f32_fp8(v.y, false), o2[2]); o2[3] = __builtin_elementwise_fma(pp, __builtin_amdgcn_cvt_pk_f32_fp8(v.y, true), o2[3]);
;         o2[4] = __builtin_elementwise_fma(pp, __builtin_amdgcn_cvt_pk_f32_fp8(v.z, false), o2[4]); o2[5] = __builtin_elementwise_fma(pp, __builtin_amdgcn_cvt_pk_f32_fp8(v.z, true), o2[5]);
;         o2[6] = __builtin_elementwise_fma(pp, __builtin_amdgcn_cvt_pk_f32_fp8(v.w, false), o2[6]); o2[7] = __builtin_elementwise_fma(pp, __builtin_amdgcn_cvt_pk_f32_fp8(v.w, true), o2[7]);
;     }
; }
	v_cvt_pk_f32_fp8_e32 v[214:215], v84
	v_cvt_pk_f32_fp8_sdwa v[216:217], v84 src0_sel:WORD_1
	v_pk_fma_f32 v[198:199], v[170:171], v[214:215], v[198:199] op_sel:[1,0,0]
	v_pk_fma_f32 v[200:201], v[170:171], v[216:217], v[200:201] op_sel:[1,0,0]
	v_cvt_pk_f32_fp8_e32 v[218:219], v85
	v_cvt_pk_f32_fp8_sdwa v[220:221], v85 src0_sel:WORD_1
	v_pk_fma_f32 v[202:203], v[170:171], v[218:219], v[202:203] op_sel:[1,0,0]
	v_pk_fma_f32 v[204:205], v[170:171], v[220:221], v[204:205] op_sel:[1,0,0]
	v_cvt_pk_f32_fp8_e32 v[214:215], v86
	v_cvt_pk_f32_fp8_sdwa v[216:217], v86 src0_sel:WORD_1
	v_pk_fma_f32 v[206:207], v[170:171], v[214:215], v[206:207] op_sel:[1,0,0]
	v_pk_fma_f32 v[208:209], v[170:171], v[216:217], v[208:209] op_sel:[1,0,0]
	v_cvt_pk_f32_fp8_e32 v[218:219], v87
	v_cvt_pk_f32_fp8_sdwa v[220:221], v87 src0_sel:WORD_1
	v_pk_fma_f32 v[210:211], v[170:171], v[218:219], v[210:211] op_sel:[1,0,0]
	v_pk_fma_f32 v[212:213], v[170:171], v[220:221], v[212:213] op_sel:[1,0,0]
	s_waitcnt lgkmcnt(0)
	v_lshl_add_u32 v166, v166, 8, v138
	v_lshl_add_u32 v167, v167, 8, v138
	v_lshl_add_u32 v168, v168, 8, v138
	v_lshl_add_u32 v169, v169, 8, v138
	buffer_load_dwordx4 v[64:67], v166, s[16:19], s26 offen sc0
	buffer_load_dwordx4 v[68:71], v167, s[16:19], s26 offen sc0
	buffer_load_dwordx4 v[72:75], v168, s[16:19], s26 offen sc0
	buffer_load_dwordx4 v[76:79], v169, s[16:19], s26 offen sc0
	s_waitcnt vmcnt(29)
	v_cvt_pk_f32_fp8_e32 v[214:215], v88
	v_cvt_pk_f32_fp8_sdwa v[216:217], v88 src0_sel:WORD_1
	v_pk_fma_f32 v[198:199], v[172:173], v[214:215], v[198:199] op_sel_hi:[0,1,1]
	v_pk_fma_f32 v[200:201], v[172:173], v[216:217], v[200:201] op_sel_hi:[0,1,1]
	v_cvt_pk_f32_fp8_e32 v[218:219], v89
	v_cvt_pk_f32_fp8_sdwa v[220:221], v89 src0_sel:WORD_1
	v_pk_fma_f32 v[202:203], v[172:173], v[218:219], v[202:203] op_sel_hi:[0,1,1]
	v_pk_fma_f32 v[204:205], v[172:173], v[220:221], v[204:205] op_sel_hi:[0,1,1]
	v_cvt_pk_f32_fp8_e32 v[214:215], v90
	v_cvt_pk_f32_fp8_sdwa v[216:217], v90 src0_sel:WORD_1
	v_pk_fma_f32 v[206:207], v[172:173], v[214:215], v[206:207] op_sel_hi:[0,1,1]
	v_pk_fma_f32 v[208:209], v[172:173], v[216:217], v[208:209] op_sel_hi:[0,1,1]
	v_cvt_pk_f32_fp8_e32 v[218:219], v91
	v_cvt_pk_f32_fp8_sdwa v[220:221], v91 src0_sel:WORD_1
	v_pk_fma_f32 v[210:211], v[172:173], v[218:219], v[210:211] op_sel_hi:[0,1,1]
	v_pk_fma_f32 v[212:213], v[172:173], v[220:221], v[212:213] op_sel_hi:[0,1,1]
	s_waitcnt vmcnt(28)
	v_cvt_pk_f32_fp8_e32 v[214:215], v92
	v_cvt_pk_f32_fp8_sdwa v[216:217], v92 src0_sel:WORD_1
	v_pk_fma_f32 v[198:199], v[172:173], v[214:215], v[198:199] op_sel:[1,0,0]
	v_pk_fma_f32 v[200:201], v[172:173], v[216:217], v[200:201] op_sel:[1,0,0]
	v_cvt_pk_f32_fp8_e32 v[218:219], v93
	v_cvt_pk_f32_fp8_sdwa v[220:221], v93 src0_sel:WORD_1
	v_pk_fma_f32 v[202:203], v[172:173], v[218:219], v[202:203] op_sel:[1,0,0]
	v_pk_fma_f32 v[204:205], v[172:173], v[220:221], v[204:205] op_sel:[1,0,0]
	v_cvt_pk_f32_fp8_e32 v[214:215], v94
	v_cvt_pk_f32_fp8_sdwa v[216:217], v94 src0_sel:WORD_1
	v_pk_fma_f32 v[206:207], v[172:173], v[214:215], v[206:207] op_sel:[1,0,0]
	v_pk_fma_f32 v[208:209], v[172:173], v[216:217], v[208:209] op_sel:[1,0,0]
	v_cvt_pk_f32_fp8_e32 v[218:219], v95
	v_cvt_pk_f32_fp8_sdwa v[220:221], v95 src0_sel:WORD_1
	v_pk_fma_f32 v[210:211], v[172:173], v[218:219], v[210:211] op_sel:[1,0,0]
	v_pk_fma_f32 v[212:213], v[172:173], v[220:221], v[212:213] op_sel:[1,0,0]
	ds_read_b128 v[170:173], v139 offset:80
	s_waitcnt vmcnt(27)
	v_cvt_pk_f32_fp8_e32 v[214:215], v96
	v_cvt_pk_f32_fp8_sdwa v[216:217], v96 src0_sel:WORD_1
	v_pk_fma_f32 v[198:199], v[174:175], v[214:215], v[198:199] op_sel_hi:[0,1,1]
	v_pk_fma_f32 v[200:201], v[174:175], v[216:217], v[200:201] op_sel_hi:[0,1,1]
	v_cvt_pk_f32_fp8_e32 v[218:219], v97
	v_cvt_pk_f32_fp8_sdwa v[220:221], v97 src0_sel:WORD_1
	v_pk_fma_f32 v[202:203], v[174:175], v[218:219], v[202:203] op_sel_hi:[0,1,1]
	v_pk_fma_f32 v[204:205], v[174:175], v[220:221], v[204:205] op_sel_hi:[0,1,1]
	v_cvt_pk_f32_fp8_e32 v[214:215], v98
	v_cvt_pk_f32_fp8_sdwa v[216:217], v98 src0_sel:WORD_1
	v_pk_fma_f32 v[206:207], v[174:175], v[214:215], v[206:207] op_sel_hi:[0,1,1]
	v_pk_fma_f32 v[208:209], v[174:175], v[216:217], v[208:209] op_sel_hi:[0,1,1]
	v_cvt_pk_f32_fp8_e32 v[218:219], v99
	v_cvt_pk_f32_fp8_sdwa v[220:221], v99 src0_sel:WORD_1
	v_pk_fma_f32 v[210:211], v[174:175], v[218:219], v[210:211] op_sel_hi:[0,1,1]
	v_pk_fma_f32 v[212:213], v[174:175], v[220:221], v[212:213] op_sel_hi:[0,1,1]
	s_waitcnt vmcnt(26)
	v_cvt_pk_f32_fp8_e32 v[214:215], v100
	v_cvt_pk_f32_fp8_sdwa v[216:217], v100 src0_sel:WORD_1
	v_pk_fma_f32 v[198:199], v[174:175], v[214:215], v[198:199] op_sel:[1,0,0]
	v_pk_fma_f32 v[200:201], v[174:175], v[216:217], v[200:201] op_sel:[1,0,0]
	v_cvt_pk_f32_fp8_e32 v[218:219], v101
	v_cvt_pk_f32_fp8_sdwa v[220:221], v101 src0_sel:WORD_1
	v_pk_fma_f32 v[202:203], v[174:175], v[218:219], v[202:203] op_sel:[1,0,0]
	v_pk_fma_f32 v[204:205], v[174:175], v[220:221], v[204:205] op_sel:[1,0,0]
	v_cvt_pk_f32_fp8_e32 v[214:215], v102
	v_cvt_pk_f32_fp8_sdwa v[216:217], v102 src0_sel:WORD_1
	v_pk_fma_f32 v[206:207], v[174:175], v[214:215], v[206:207] op_sel:[1,0,0]
	v_pk_fma_f32 v[208:209], v[174:175], v[216:217], v[208:209] op_sel:[1,0,0]
	v_cvt_pk_f32_fp8_e32 v[218:219], v103
	v_cvt_pk_f32_fp8_sdwa v[220:221], v103 src0_sel:WORD_1
	v_pk_fma_f32 v[210:211], v[174:175], v[218:219], v[210:211] op_sel:[1,0,0]
	v_pk_fma_f32 v[212:213], v[174:175], v[220:221], v[212:213] op_sel:[1,0,0]
	s_waitcnt lgkmcnt(0)
; #define LAS __attribute__((address_space(3)))
; __device__ __forceinline__ void kv8_issue(u32x4 (&buf)[8], __amdgpu_buffer_rsrc_t rs, int voff  , int sbase  , const int (&iv)[4], int b) {
;     const int jj = b >> 3, l0 = (b & 7) * 8;
;     const int ivb = (jj == 0) ? iv[0] : (jj == 1) ? iv[1] : (jj == 2) ? iv[2] : iv[3];
; #pragma unroll
;     for (int u = 0; u < 8; ++u) { const int si = __builtin_amdgcn_readlane(ivb, l0 + u); buf[u] = __builtin_amdgcn_raw_buffer_load_b128(rs, voff, si * 2048 + sbase, KV8_AUX); }
; }
; __device__ __forceinline__ void kv8_pv(const u32x4 (&buf)[8], f32x2v (&o2)[8], const LAS float* srow, int b) {
;     const LAS f32x4* p4 = (const LAS f32x4*)(srow + b * 8);
;     const f32x4 p0 = p4[0], p1 = p4[1];
;     const float p[8] = {p0.x, p0.y, p0.z, p0.w, p1.x, p1.y, p1.z, p1.w};
; #pragma unroll
;     for (int u = 0; u < 8; ++u) {
;         const u32x4 v = buf[u]; const f32x2v pp = {p[u], p[u]};
;         o2[0] = __builtin_elementwise_fma(pp, __builtin_amdgcn_cvt_pk_f32_fp8(v.x, false), o2[0]); o2[1] = __builtin_elementwise_fma(pp, __builtin_amdgcn_cvt_pk_f32_fp8(v.x, true), o2[1]);
;         o2[2] = __builtin_elementwise_fma(pp, __builtin_amdgcn_cvt_pk_f32_fp8(v.y, false), o2[2]); o2[3] = __builtin_elementwise_fma(pp, __builtin_amdgcn_cvt_pk_f32_fp8(v.y, true), o2[3]);
;         o2[4] = __builtin_elementwise_fma(pp, __builtin_amdgcn_cvt_pk_f32_fp8(v.z, false), o2[4]); o2[5] = __builtin_elementwise_fma(pp, __builtin_amdgcn_cvt_pk_f32_fp8(v.z, true), o2[5]);
;         o2[6] = __builtin_elementwise_fma(pp, __builtin_amdgcn_cvt_pk_f32_fp8(v.w, false), o2[6]); o2[7] = __builtin_elementwise_fma(pp, __builtin_amdgcn_cvt_pk_f32_fp8(v.w, true), o2[7]);
;     }
; }
	v_lshl_add_u32 v170, v170, 8, v138
	v_lshl_add_u32 v171, v171, 8, v138
	v_lshl_add_u32 v172, v172, 8, v138
	v_lshl_add_u32 v173, v173, 8, v138
	buffer_load_dwordx4 v[80:83], v170, s[16:19], s26 offen sc0
	buffer_load_dwordx4 v[84:87], v171, s[16:19], s26 offen sc0
	buffer_load_dwordx4 v[88:91], v172, s[16:19], s26 offen sc0
	buffer_load_dwordx4 v[92:95], v173, s[16:19], s26 offen sc0
	s_waitcnt vmcnt(29)
	v_cvt_pk_f32_fp8_e32 v[214:215], v104
	v_cvt_pk_f32_fp8_sdwa v[216:217], v104 src0_sel:WORD_1
	v_pk_fma_f32 v[198:199], v[176:177], v[214:215], v[198:199] op_sel_hi:[0,1,1]
	v_pk_fma_f32 v[200:201], v[176:177], v[216:217], v[200:201] op_sel_hi:[0,1,1]
	v_cvt_pk_f32_fp8_e32 v[218:219], v105
	v_cvt_pk_f32_fp8_sdwa v[220:221], v105 src0_sel:WORD_1
	v_pk_fma_f32 v[202:203], v[176:177], v[218:219], v[202:203] op_sel_hi:[0,1,1]
	v_pk_fma_f32 v[204:205], v[176:177], v[220:221], v[204:205] op_sel_hi:[0,1,1]
	v_cvt_pk_f32_fp8_e32 v[214:215], v106
	v_cvt_pk_f32_fp8_sdwa v[216:217], v106 src0_sel:WORD_1
	v_pk_fma_f32 v[206:207], v[176:177], v[214:215], v[206:207] op_sel_hi:[0,1,1]
	v_pk_fma_f32 v[208:209], v[176:177], v[216:217], v[208:209] op_sel_hi:[0,1,1]
	v_cvt_pk_f32_fp8_e32 v[218:219], v107
	v_cvt_pk_f32_fp8_sdwa v[220:221], v107 src0_sel:WORD_1
	v_pk_fma_f32 v[210:211], v[176:177], v[218:219], v[210:211] op_sel_hi:[0,1,1]
	v_pk_fma_f32 v[212:213], v[176:177], v[220:221], v[212:213] op_sel_hi:[0,1,1]
	s_waitcnt vmcnt(28)
	v_cvt_pk_f32_fp8_e32 v[214:215], v108
	v_cvt_pk_f32_fp8_sdwa v[216:217], v108 src0_sel:WORD_1
	v_pk_fma_f32 v[198:199], v[176:177], v[214:215], v[198:199] op_sel:[1,0,0]
	v_pk_fma_f32 v[200:201], v[176:177], v[216:217], v[200:201] op_sel:[1,0,0]
	v_cvt_pk_f32_fp8_e32 v[218:219], v109
	v_cvt_pk_f32_fp8_sdwa v[220:221], v109 src0_sel:WORD_1
	v_pk_fma_f32 v[202:203], v[176:177], v[218:219], v[202:203] op_sel:[1,0,0]
	v_pk_fma_f32 v[204:205], v[176:177], v[220:221], v[204:205] op_sel:[1,0,0]
	v_cvt_pk_f32_fp8_e32 v[214:215], v110
	v_cvt_pk_f32_fp8_sdwa v[216:217], v110 src0_sel:WORD_1
	v_pk_fma_f32 v[206:207], v[176:177], v[214:215], v[206:207] op_sel:[1,0,0]
	v_pk_fma_f32 v[208:209], v[176:177], v[216:217], v[208:209] op_sel:[1,0,0]
	v_cvt_pk_f32_fp8_e32 v[218:219], v111
	v_cvt_pk_f32_fp8_sdwa v[220:221], v111 src0_sel:WORD_1
	v_pk_fma_f32 v[210:211], v[176:177], v[218:219], v[210:211] op_sel:[1,0,0]
	v_pk_fma_f32 v[212:213], v[176:177], v[220:221], v[212:213] op_sel:[1,0,0]
	ds_read_b128 v[174:177], v139 offset:96
	s_waitcnt vmcnt(27)
	v_cvt_pk_f32_fp8_e32 v[214:215], v112
	v_cvt_pk_f32_fp8_sdwa v[216:217], v112 src0_sel:WORD_1
	v_pk_fma_f32 v[198:199], v[178:179], v[214:215], v[198:199] op_sel_hi:[0,1,1]
	v_pk_fma_f32 v[200:201], v[178:179], v[216:217], v[200:201] op_sel_hi:[0,1,1]
	v_cvt_pk_f32_fp8_e32 v[218:219], v113
	v_cvt_pk_f32_fp8_sdwa v[220:221], v113 src0_sel:WORD_1
	v_pk_fma_f32 v[202:203], v[178:179], v[218:219], v[202:203] op_sel_hi:[0,1,1]
	v_pk_fma_f32 v[204:205], v[178:179], v[220:221], v[204:205] op_sel_hi:[0,1,1]
	v_cvt_pk_f32_fp8_e32 v[214:215], v114
	v_cvt_pk_f32_fp8_sdwa v[216:217], v114 src0_sel:WORD_1
	v_pk_fma_f32 v[206:207], v[178:179], v[214:215], v[206:207] op_sel_hi:[0,1,1]
	v_pk_fma_f32 v[208:209], v[178:179], v[216:217], v[208:209] op_sel_hi:[0,1,1]
	v_cvt_pk_f32_fp8_e32 v[218:219], v115
	v_cvt_pk_f32_fp8_sdwa v[220:221], v115 src0_sel:WORD_1
	v_pk_fma_f32 v[210:211], v[178:179], v[218:219], v[210:211] op_sel_hi:[0,1,1]
	v_pk_fma_f32 v[212:213], v[178:179], v[220:221], v[212:213] op_sel_hi:[0,1,1]
	s_waitcnt vmcnt(26)
	v_cvt_pk_f32_fp8_e32 v[214:215], v116
	v_cvt_pk_f32_fp8_sdwa v[216:217], v116 src0_sel:WORD_1
	v_pk_fma_f32 v[198:199], v[178:179], v[214:215], v[198:199] op_sel:[1,0,0]
	v_pk_fma_f32 v[200:201], v[178:179], v[216:217], v[200:201] op_sel:[1,0,0]
	v_cvt_pk_f32_fp8_e32 v[218:219], v117
	v_cvt_pk_f32_fp8_sdwa v[220:221], v117 src0_sel:WORD_1
	v_pk_fma_f32 v[202:203], v[178:179], v[218:219], v[202:203] op_sel:[1,0,0]
	v_pk_fma_f32 v[204:205], v[178:179], v[220:221], v[204:205] op_sel:[1,0,0]
	v_cvt_pk_f32_fp8_e32 v[214:215], v118
	v_cvt_pk_f32_fp8_sdwa v[216:217], v118 src0_sel:WORD_1
	v_pk_fma_f32 v[206:207], v[178:179], v[214:215], v[206:207] op_sel:[1,0,0]
	v_pk_fma_f32 v[208:209], v[178:179], v[216:217], v[208:209] op_sel:[1,0,0]
	v_cvt_pk_f32_fp8_e32 v[218:219], v119
	v_cvt_pk_f32_fp8_sdwa v[220:221], v119 src0_sel:WORD_1
	v_pk_fma_f32 v[210:211], v[178:179], v[218:219], v[210:211] op_sel:[1,0,0]
	v_pk_fma_f32 v[212:213], v[178:179], v[220:221], v[212:213] op_sel:[1,0,0]
	s_waitcnt lgkmcnt(0)
	v_lshl_add_u32 v174, v174, 8, v138
	v_lshl_add_u32 v175, v175, 8, v138
	v_lshl_add_u32 v176, v176, 8, v138
	v_lshl_add_u32 v177, v177, 8, v138
	buffer_load_dwordx4 v[96:99], v174, s[16:19], s26 offen sc0
	buffer_load_dwordx4 v[100:103], v175, s[16:19], s26 offen sc0
	buffer_load_dwordx4 v[104:107], v176, s[16:19], s26 offen sc0
	buffer_load_dwordx4 v[108:111], v177, s[16:19], s26 offen sc0
	s_waitcnt vmcnt(29)
	v_cvt_pk_f32_fp8_e32 v[214:215], v120
	v_cvt_pk_f32_fp8_sdwa v[216:217], v120 src0_sel:WORD_1
	v_pk_fma_f32 v[198:199], v[180:181], v[214:215], v[198:199] op_sel_hi:[0,1,1]
	v_pk_fma_f32 v[200:201], v[180:181], v[216:217], v[200:201] op_sel_hi:[0,1,1]
	v_cvt_pk_f32_fp8_e32 v[218:219], v121
	v_cvt_pk_f32_fp8_sdwa v[220:221], v121 src0_sel:WORD_1
	v_pk_fma_f32 v[202:203], v[180:181], v[218:219], v[202:203] op_sel_hi:[0,1,1]
	v_pk_fma_f32 v[204:205], v[180:181], v[220:221], v[204:205] op_sel_hi:[0,1,1]
	v_cvt_pk_f32_fp8_e32 v[214:215], v122
	v_cvt_pk_f32_fp8_sdwa v[216:217], v122 src0_sel:WORD_1
	v_pk_fma_f32 v[206:207], v[180:181], v[214:215], v[206:207] op_sel_hi:[0,1,1]
	v_pk_fma_f32 v[208:209], v[180:181], v[216:217], v[208:209] op_sel_hi:[0,1,1]
	v_cvt_pk_f32_fp8_e32 v[218:219], v123
	v_cvt_pk_f32_fp8_sdwa v[220:221], v123 src0_sel:WORD_1
	v_pk_fma_f32 v[210:211], v[180:181], v[218:219], v[210:211] op_sel_hi:[0,1,1]
	v_pk_fma_f32 v[212:213], v[180:181], v[220:221], v[212:213] op_sel_hi:[0,1,1]
	s_waitcnt vmcnt(28)
; __device__ __forceinline__ unsigned cvt_pk_bf16(float lo, float hi) { unsigned r; asm volatile("v_cvt_pk_bf16_f32 %0, %1, %2" : "=v"(r) : "v"(lo), "v"(hi)); return r; }
; #define LAS __attribute__((address_space(3)))
; #define LDS_WAIT() asm volatile("s_waitcnt lgkmcnt(0)" ::: "memory")
; __device__ __forceinline__ void kv8_pv(const u32x4 (&buf)[8], f32x2v (&o2)[8], const LAS float* srow, int b) {
;     const LAS f32x4* p4 = (const LAS f32x4*)(srow + b * 8);
;     const f32x4 p0 = p4[0], p1 = p4[1];
;     const float p[8] = {p0.x, p0.y, p0.z, p0.w, p1.x, p1.y, p1.z, p1.w};
; #pragma unroll
;     for (int u = 0; u < 8; ++u) {
;         const u32x4 v = buf[u]; const f32x2v pp = {p[u], p[u]};
;         o2[0] = __builtin_elementwise_fma(pp, __builtin_amdgcn_cvt_pk_f32_fp8(v.x, false), o2[0]); o2[1] = __builtin_elementwise_fma(pp, __builtin_amdgcn_cvt_pk_f32_fp8(v.x, true), o2[1]);
;         o2[2] = __builtin_elementwise_fma(pp, __builtin_amdgcn_cvt_pk_f32_fp8(v.y, false), o2[2]); o2[3] = __builtin_elementwise_fma(pp, __builtin_amdgcn_cvt_pk_f32_fp8(v.y, true), o2[3]);
;         o2[4] = __builtin_elementwise_fma(pp, __builtin_amdgcn_cvt_pk_f32_fp8(v.z, false), o2[4]); o2[5] = __builtin_elementwise_fma(pp, __builtin_amdgcn_cvt_pk_f32_fp8(v.z, true), o2[5]);
;         o2[6] = __builtin_elementwise_fma(pp, __builtin_amdgcn_cvt_pk_f32_fp8(v.w, false), o2[6]); o2[7] = __builtin_elementwise_fma(pp, __builtin_amdgcn_cvt_pk_f32_fp8(v.w, true), o2[7]);
;     }
; }
; __device__ __forceinline__ void attn_query8(const unsigned char* __restrict__ KV8, const bf16_t* __restrict__ Z, const int* __restrict__ SEL, bf16_t* __restrict__ YMIX, int t, LAS float* sbuf  ) {
;     ...
;     u32x4 o0, o1;
;     o0.x = cvt_pk_bf16(o[0].x, o[0].y); o0.y = cvt_pk_bf16(o[1].x, o[1].y); o0.z = cvt_pk_bf16(o[2].x, o[2].y); o0.w = cvt_pk_bf16(o[3].x, o[3].y);
;     o1.x = cvt_pk_bf16(o[4].x, o[4].y); o1.y = cvt_pk_bf16(o[5].x, o[5].y); o1.z = cvt_pk_bf16(o[6].x, o[6].y); o1.w = cvt_pk_bf16(o[7].x, o[7].y);
;     u32x4* yp = (u32x4*)(YMIX + (size_t)t * D_ + 1024 + lane * 16);
;     yp[0] = o0; yp[1] = o1;
;     LDS_WAIT();
	v_cvt_pk_f32_fp8_e32 v[214:215], v124
	v_cvt_pk_f32_fp8_sdwa v[216:217], v124 src0_sel:WORD_1
	v_pk_fma_f32 v[198:199], v[180:181], v[214:215], v[198:199] op_sel:[1,0,0]
	v_pk_fma_f32 v[200:201], v[180:181], v[216:217], v[200:201] op_sel:[1,0,0]
	v_cvt_pk_f32_fp8_e32 v[218:219], v125
	v_cvt_pk_f32_fp8_sdwa v[220:221], v125 src0_sel:WORD_1
	v_pk_fma_f32 v[202:203], v[180:181], v[218:219], v[202:203] op_sel:[1,0,0]
	v_pk_fma_f32 v[204:205], v[180:181], v[220:221], v[204:205] op_sel:[1,0,0]
	v_cvt_pk_f32_fp8_e32 v[214:215], v126
	v_cvt_pk_f32_fp8_sdwa v[216:217], v126 src0_sel:WORD_1
	v_pk_fma_f32 v[206:207], v[180:181], v[214:215], v[206:207] op_sel:[1,0,0]
	v_pk_fma_f32 v[208:209], v[180:181], v[216:217], v[208:209] op_sel:[1,0,0]
	v_cvt_pk_f32_fp8_e32 v[218:219], v127
	v_cvt_pk_f32_fp8_sdwa v[220:221], v127 src0_sel:WORD_1
	v_pk_fma_f32 v[210:211], v[180:181], v[218:219], v[210:211] op_sel:[1,0,0]
	v_pk_fma_f32 v[212:213], v[180:181], v[220:221], v[212:213] op_sel:[1,0,0]
	ds_read_b128 v[178:181], v139 offset:112
	v_add_f32_dpp v198, v198, v198 row_ror:8 row_mask:0xf bank_mask:0x3
	v_add_f32_dpp v199, v199, v199 row_ror:8 row_mask:0xf bank_mask:0x3
	v_add_f32_dpp v200, v200, v200 row_ror:8 row_mask:0xf bank_mask:0x3
	v_add_f32_dpp v201, v201, v201 row_ror:8 row_mask:0xf bank_mask:0x3
	v_add_f32_dpp v202, v202, v202 row_ror:8 row_mask:0xf bank_mask:0x3
	v_add_f32_dpp v203, v203, v203 row_ror:8 row_mask:0xf bank_mask:0x3
	v_add_f32_dpp v204, v204, v204 row_ror:8 row_mask:0xf bank_mask:0x3
	v_add_f32_dpp v205, v205, v205 row_ror:8 row_mask:0xf bank_mask:0x3
	v_add_f32_dpp v206, v206, v206 row_ror:8 row_mask:0xf bank_mask:0xc
	v_add_f32_dpp v207, v207, v207 row_ror:8 row_mask:0xf bank_mask:0xc
	v_add_f32_dpp v208, v208, v208 row_ror:8 row_mask:0xf bank_mask:0xc
	v_add_f32_dpp v209, v209, v209 row_ror:8 row_mask:0xf bank_mask:0xc
	v_add_f32_dpp v210, v210, v210 row_ror:8 row_mask:0xf bank_mask:0xc
	v_add_f32_dpp v211, v211, v211 row_ror:8 row_mask:0xf bank_mask:0xc
	v_add_f32_dpp v212, v212, v212 row_ror:8 row_mask:0xf bank_mask:0xc
	v_add_f32_dpp v213, v213, v213 row_ror:8 row_mask:0xf bank_mask:0xc
	v_mov_b32_dpp v198, v206 quad_perm:[0,1,2,3] row_mask:0xf bank_mask:0xc
	v_mov_b32_dpp v199, v207 quad_perm:[0,1,2,3] row_mask:0xf bank_mask:0xc
	v_mov_b32_dpp v200, v208 quad_perm:[0,1,2,3] row_mask:0xf bank_mask:0xc
	v_mov_b32_dpp v201, v209 quad_perm:[0,1,2,3] row_mask:0xf bank_mask:0xc
	v_mov_b32_dpp v202, v210 quad_perm:[0,1,2,3] row_mask:0xf bank_mask:0xc
	v_mov_b32_dpp v203, v211 quad_perm:[0,1,2,3] row_mask:0xf bank_mask:0xc
	v_mov_b32_dpp v204, v212 quad_perm:[0,1,2,3] row_mask:0xf bank_mask:0xc
	v_mov_b32_dpp v205, v213 quad_perm:[0,1,2,3] row_mask:0xf bank_mask:0xc
	s_waitcnt lgkmcnt(0)
	v_lshl_add_u32 v178, v178, 8, v138
	v_lshl_add_u32 v179, v179, 8, v138
	v_lshl_add_u32 v180, v180, 8, v138
	v_lshl_add_u32 v181, v181, 8, v138
	buffer_load_dwordx4 v[112:115], v178, s[16:19], s26 offen sc0
	buffer_load_dwordx4 v[116:119], v179, s[16:19], s26 offen sc0
	buffer_load_dwordx4 v[120:123], v180, s[16:19], s26 offen sc0
	buffer_load_dwordx4 v[124:127], v181, s[16:19], s26 offen sc0
	ds_bpermute_b32 v214, v140, v198
	ds_bpermute_b32 v215, v140, v199
	ds_bpermute_b32 v216, v140, v200
	ds_bpermute_b32 v217, v140, v201
	ds_bpermute_b32 v218, v140, v202
	ds_bpermute_b32 v219, v140, v203
	ds_bpermute_b32 v220, v140, v204
	ds_bpermute_b32 v221, v140, v205
	s_waitcnt lgkmcnt(0)
	v_add_f32_e32 v198, v198, v214
	v_add_f32_e32 v199, v199, v215
	v_add_f32_e32 v200, v200, v216
	v_add_f32_e32 v201, v201, v217
	v_add_f32_e32 v202, v202, v218
	v_add_f32_e32 v203, v203, v219
	v_add_f32_e32 v204, v204, v220
	v_add_f32_e32 v205, v205, v221
	ds_bpermute_b32 v214, v141, v198
	ds_bpermute_b32 v215, v141, v199
	ds_bpermute_b32 v216, v141, v200
	ds_bpermute_b32 v217, v141, v201
	ds_bpermute_b32 v218, v141, v202
	ds_bpermute_b32 v219, v141, v203
	ds_bpermute_b32 v220, v141, v204
	ds_bpermute_b32 v221, v141, v205
	s_waitcnt lgkmcnt(0)
	v_add_f32_e32 v198, v198, v214
	v_add_f32_e32 v199, v199, v215
	v_add_f32_e32 v200, v200, v216
	v_add_f32_e32 v201, v201, v217
	v_add_f32_e32 v202, v202, v218
	v_add_f32_e32 v203, v203, v219
	v_add_f32_e32 v204, v204, v220
	v_add_f32_e32 v205, v205, v221
	s_ashr_i32 s81, s80, 31
	s_lshl_b64 s[10:11], s[80:81], 12
	s_add_u32 s10, s14, s10
	s_addc_u32 s11, s15, s11
	v_mul_f32_e32 v198, v198, v149
	v_mul_f32_e32 v199, v199, v149
	v_mul_f32_e32 v200, v200, v149
	v_mul_f32_e32 v201, v201, v149
	v_mul_f32_e32 v202, v202, v149
	v_mul_f32_e32 v203, v203, v149
	v_mul_f32_e32 v204, v204, v149
	v_mul_f32_e32 v205, v205, v149
	v_cvt_pk_bf16_f32 v214, v198, v199
	v_cvt_pk_bf16_f32 v215, v200, v201
	v_cvt_pk_bf16_f32 v216, v202, v203
	v_cvt_pk_bf16_f32 v217, v204, v205
	v_cmp_gt_u32_e32 vcc, 16, v144
	s_and_saveexec_b64 s[12:13], vcc
	global_store_dwordx4 v238, v[214:217], s[10:11] offset:2048
	s_mov_b64 exec, s[12:13]
	s_addk_i32 s80, 0x100
	s_cmpk_gt_i32 s80, 0x3fff
	s_cbranch_scc0 .Latt_unit
	s_waitcnt vmcnt(0)
